# hybrid barriers at P2->P3 and P10->P11: group-local wait for the reads, full barrier only arrived at and completed before the next phase's first epilogue store
# baseline (speedup 1.0000x reference)
.LBB0_555:
	s_mov_b32 s101, -1
	s_getreg_b32 s6, hwreg(HW_REG_XCC_ID, 0, 4)
	s_waitcnt vmcnt(0)
	s_waitcnt lgkmcnt(0)
	s_barrier
	s_and_saveexec_b64 s[0:1], s[46:47]
	s_cbranch_execz .LBB0_607
	s_add_i32 s7, 0, 0x20160
	v_mov_b32_e32 v0, s7
	s_waitcnt vmcnt(0) expcnt(0) lgkmcnt(0)
	ds_read_b32 v2, v0
	s_add_i32 s7, 0, 0x20164
	v_mov_b32_e32 v0, s7
	ds_read_b32 v0, v0
	s_and_b32 s58, s6, 15
	s_waitcnt lgkmcnt(1)
	v_cmp_ne_u32_e32 vcc, 0, v2
	s_cbranch_vccnz .LBB0_571
	s_add_u32 s6, s66, 0x1200
	s_addc_u32 s7, s67, 0
	s_add_u32 s8, s66, 0x1400
	s_addc_u32 s9, s67, 0
	s_add_u32 s10, s66, 0x1500
	s_addc_u32 s11, s67, 0
	s_add_u32 s12, s66, 0x1600
	s_addc_u32 s13, s67, 0
	s_add_u32 s16, s66, 0x1700
	s_addc_u32 s17, s67, 0
	s_add_u32 s18, s66, 0x1800
	s_addc_u32 s19, s67, 0
	s_add_u32 s20, s66, 0x1900
	s_addc_u32 s21, s67, 0
	s_add_u32 s22, s66, 0x1a00
	s_addc_u32 s23, s67, 0
	s_add_u32 s24, s66, 0x1b00
	s_addc_u32 s25, s67, 0
	s_add_u32 s26, s66, 0x1c00
	s_addc_u32 s27, s67, 0
	s_add_u32 s28, s66, 0x1d00
	s_addc_u32 s29, s67, 0
	s_add_u32 s30, s66, 0x1e00
	s_addc_u32 s31, s67, 0
	s_add_u32 s34, s66, 0x1f00
	s_addc_u32 s35, s67, 0
	s_add_u32 s36, s66, 0x2000
	s_addc_u32 s37, s67, 0
	s_add_u32 s38, s66, 0x2100
	s_addc_u32 s39, s67, 0
	s_add_u32 s40, s66, 0x2200
	s_addc_u32 s41, s67, 0
	s_mul_i32 s59, s65, s74
	s_add_u32 s42, s66, 0x2300
	s_mul_i32 s59, s59, s64
	s_addc_u32 s43, s67, 0
	s_mov_b32 s60, 1
	v_mov_b32_e32 v16, 0
	s_branch .LBB0_559

.LBB0_573:
	s_or_b64 exec, exec, s[10:11]
	v_cvt_f32_u32_e32 v4, v2
	s_waitcnt vmcnt(0)
	v_readfirstlane_b32 s8, v3
	v_sub_u32_e32 v3, 0, v2
	v_rcp_iflag_f32_e32 v4, v4
	v_add_u32_e32 v5, s8, v1
	v_mul_f32_e32 v4, 0x4f7ffffe, v4
	v_cvt_u32_f32_e32 v4, v4
	v_mul_lo_u32 v1, v3, v4
	v_mul_hi_u32 v1, v4, v1
	v_add_u32_e32 v1, v4, v1
	v_mul_hi_u32 v1, v5, v1
	v_mul_lo_u32 v3, v1, v2
	v_sub_u32_e32 v3, v5, v3
	v_add_u32_e32 v4, 1, v1
	v_cmp_ge_u32_e32 vcc, v3, v2
	s_nop 1
	v_cndmask_b32_e32 v1, v1, v4, vcc
	v_sub_u32_e32 v4, v3, v2
	v_cndmask_b32_e32 v3, v3, v4, vcc
	v_add_u32_e32 v4, 1, v1
	v_cmp_ge_u32_e32 vcc, v3, v2
	v_add_u32_e32 v3, 1, v5
	s_nop 0
	v_cndmask_b32_e32 v1, v1, v4, vcc
	v_mul_lo_u32 v4, v2, v1
	v_add_u32_e32 v2, v4, v2
	v_cmp_ne_u32_e32 vcc, v3, v2
	s_and_saveexec_b64 s[8:9], vcc
	s_xor_b64 s[8:9], exec, s[8:9]
	s_cbranch_execz .LBB0_587
	s_cmp_lt_u32 s2, 0
	s_cbranch_scc1 .Lsb_wait_h0
	s_cmp_lg_u32 s64, 0x100
	s_cbranch_scc1 .Lsb_wait_h0
	s_cmp_lg_u32 s100, 1
	s_cbranch_scc1 .Lsb_wait_h0
	v_readfirstlane_b32 s101, v1
	s_branch .LBB0_587
.Lsb_wait_h0:
	s_waitcnt lgkmcnt(0)
	buffer_inv sc1
	v_mov_b32_e32 v0, 0x2000
	global_load_dword v0, v0, s[6:7] offset:1024 sc1
	s_add_u32 s16, s6, 0x2400
	s_addc_u32 s17, s7, 0
	s_waitcnt vmcnt(0)
	v_cmp_eq_u32_e32 vcc, v0, v1
	s_and_saveexec_b64 s[10:11], vcc
	s_cbranch_execz .LBB0_586
	s_add_u32 s12, s66, 0x1200
	s_addc_u32 s13, s67, 0
	s_mov_b32 s28, 1
	s_mov_b64 s[18:19], 0
	v_mov_b32_e32 v0, 0
	s_branch .LBB0_577

.LBB0_607:
	s_or_b64 exec, exec, s[0:1]
	s_cmp_eq_u32 s100, 1
	s_cbranch_scc0 .Lhb_skip_1
	s_and_saveexec_b64 s[0:1], s[46:47]
	s_cbranch_execz .Lhb_done_1
	s_and_b32 s98, s2, 7
	s_lshl_b32 s98, s98, 6
	s_add_i32 s98, s98, 0x4a00
	v_mov_b32_e32 v250, s98
	v_mov_b32_e32 v251, 1
	global_atomic_add v252, v250, v251, s[66:67] sc0
	buffer_inv sc1
	s_lshr_b32 s98, s64, 3
	s_mul_i32 s98, s98, 2
	s_add_i32 s98, s98, -1
	v_add_u32_e32 v250, 0x200, v250
	s_waitcnt vmcnt(0)
	v_readfirstlane_b32 s99, v252
	s_cmp_eq_u32 s99, s98
	s_cbranch_scc0 .Lhb_wait_1
	global_atomic_add v250, v251, s[66:67]
	s_waitcnt vmcnt(0)
	s_branch .Lhb_done_1

.Lhb_skip_1:
	s_mov_b64 s[6:7], s[66:67]
	s_mov_b64 s[0:1], s[68:69]
	s_waitcnt lgkmcnt(0)
	v_mov_b32_e32 v0, v194
	s_mov_b32 s44, s64
	v_mov_b32_e32 v8, v194
	s_cmpk_lt_i32 s2, 0x200
	s_barrier
	s_cselect_b64 s[12:13], -1, 0
	s_cmpk_gt_i32 s2, 0x1ff
	v_readfirstlane_b32 s26, v8
	s_cbranch_scc1 .LBB0_613
	s_lshr_b32 s0, s3, 29
	s_add_i32 s8, s2, s0
	s_and_b32 s0, s8, -8
	s_sub_i32 s9, s2, s0
	s_cmp_gt_i32 s9, -1
	s_cbranch_scc0 .LBB0_610
	s_lshl_b32 s10, s9, 6
	s_cbranch_execz .LBB0_611
	s_branch .LBB0_612

.Lsb_cj_h0:
	s_barrier
	s_lshl_b32 s31, s10, 8
	s_add_i32 s31, s31, s62
	v_or_b32_e32 v152, s31, v139
	v_ashrrev_i32_e32 v153, 31, v152
	v_lshlrev_b64 v[154:155], 6, v[152:153]
	v_lshl_add_u64 v[154:155], s[22:23], 0, v[154:155]
	global_load_dwordx4 v[162:165], v[154:155], off
	global_load_dwordx4 v[166:169], v[154:155], off offset:16
	global_load_dwordx4 v[170:173], v[154:155], off offset:32
	global_load_dwordx4 v[174:177], v[154:155], off offset:48
	s_cmp_gt_i32 s0, 1
	s_cselect_b64 s[38:39], -1, 0
	s_lshl_b32 s29, s0, 8
	s_and_b64 s[0:1], exec, s[38:39]
	s_mov_b64 s[10:11], -1
	v_lshlrev_b32_e32 v136, 1, v138
	s_add_i32 s12, s29, 0xfffffe00
	s_waitcnt vmcnt(0)
	v_mov_b32_e32 v154, v163
	v_mov_b32_e32 v155, v164
	v_mov_b32_e32 v163, v165
	v_mov_b32_e32 v164, v167
	v_mov_b32_e32 v165, v168
	v_mov_b32_e32 v167, v169
	v_pk_add_f32 v[154:155], v[154:155], v[162:163]
	v_pk_add_f32 v[162:163], v[164:165], v[166:167]
	v_pk_add_f32 v[154:155], v[154:155], v[154:155] op_sel:[0,1] op_sel_hi:[1,0]
	v_pk_add_f32 v[162:163], v[162:163], v[162:163] op_sel:[0,1] op_sel_hi:[1,0]
	v_add_f32_e32 v168, v170, v171
	v_add_f32_e32 v170, v172, v173
	v_mov_b32_e32 v169, v176
	v_mov_b32_e32 v171, v177
	v_mov_b32_e32 v155, v174
	v_mov_b32_e32 v163, v175
	v_pk_add_f32 v[164:165], v[168:169], v[170:171]
	v_pk_add_f32 v[154:155], v[154:155], v[162:163]
	s_nop 0
	v_pk_add_f32 v[154:155], v[154:155], v[164:165]
	s_nop 0
	v_add_f32_e32 v153, v154, v155
	v_fmamk_f32 v153, v153, 0x3a800000, v160
	v_mul_f32_e32 v154, 0x4b800000, v153
	v_cmp_gt_f32_e32 vcc, s78, v153
	s_nop 1
	v_cndmask_b32_e32 v153, v153, v154, vcc
	v_rsq_f32_e32 v153, v153
	s_nop 0
	v_mul_f32_e32 v154, 0x45800000, v153
	v_cndmask_b32_e32 v154, v153, v154, vcc
	v_pk_mul_f32 v[162:163], v[122:123], v[154:155] op_sel_hi:[1,0]
	v_pk_mul_f32 v[122:123], v[120:121], v[154:155] op_sel_hi:[1,0]
	s_mov_b64 vcc, s[0:1]
	v_pk_mul_f32 v[126:127], v[126:127], v[154:155] op_sel_hi:[1,0]
	v_pk_mul_f32 v[124:125], v[124:125], v[154:155] op_sel_hi:[1,0]
	s_nop 0
	v_cvt_pk_bf16_f32 v120, v124, v125
	v_cvt_pk_bf16_f32 v121, v126, v127
	v_cvt_pk_bf16_f32 v122, v122, v123
	v_cvt_pk_bf16_f32 v123, v162, v163
	s_cbranch_vccz .LBB0_631
	v_mov_b64_e32 v[124:125], s[18:19]
	v_mad_i64_i32 v[124:125], s[0:1], v152, s80, v[124:125]
	v_lshl_add_u64 v[124:125], s[12:13], 1, v[124:125]
	s_lshl_b32 s0, s63, 1
	s_mov_b32 s1, s13
	v_lshl_add_u64 v[124:125], v[124:125], 0, s[0:1]
	v_lshl_add_u64 v[124:125], v[124:125], 0, v[136:137]
	global_store_dwordx4 v[124:125], v[120:123], off
	s_mov_b64 s[10:11], 0

.LBB0_1648:
	s_mov_b32 s101, -1
	s_getreg_b32 s6, hwreg(HW_REG_XCC_ID, 0, 4)
	s_waitcnt vmcnt(0)
	s_waitcnt lgkmcnt(0)
	s_barrier
	s_and_saveexec_b64 s[0:1], s[46:47]
	s_cbranch_execz .LBB0_1700
	s_add_i32 s7, 0, 0x20160
	v_mov_b32_e32 v0, s7
	s_waitcnt vmcnt(0) expcnt(0) lgkmcnt(0)
	ds_read_b32 v2, v0
	s_add_i32 s7, 0, 0x20164
	v_mov_b32_e32 v0, s7
	ds_read_b32 v0, v0
	s_and_b32 s51, s6, 15
	s_waitcnt lgkmcnt(1)
	v_cmp_ne_u32_e32 vcc, 0, v2
	s_cbranch_vccnz .LBB0_1664
	s_add_u32 s6, s66, 0x1200
	s_addc_u32 s7, s67, 0
	s_add_u32 s14, s66, 0x1400
	s_addc_u32 s15, s67, 0
	s_add_u32 s16, s66, 0x1500
	s_addc_u32 s17, s67, 0
	s_add_u32 s18, s66, 0x1600
	s_addc_u32 s19, s67, 0
	s_add_u32 s20, s66, 0x1700
	s_addc_u32 s21, s67, 0
	s_add_u32 s22, s66, 0x1800
	s_addc_u32 s23, s67, 0
	s_add_u32 s24, s66, 0x1900
	s_addc_u32 s25, s67, 0
	s_add_u32 s26, s66, 0x1a00
	s_addc_u32 s27, s67, 0
	s_add_u32 s28, s66, 0x1b00
	s_addc_u32 s29, s67, 0
	s_add_u32 s30, s66, 0x1c00
	s_addc_u32 s31, s67, 0
	s_add_u32 s34, s66, 0x1d00
	s_addc_u32 s35, s67, 0
	s_add_u32 s36, s66, 0x1e00
	s_addc_u32 s37, s67, 0
	s_add_u32 s38, s66, 0x1f00
	s_addc_u32 s39, s67, 0
	s_add_u32 s40, s66, 0x2000
	s_addc_u32 s41, s67, 0
	s_add_u32 s42, s66, 0x2100
	s_addc_u32 s43, s67, 0
	s_add_u32 s44, s66, 0x2200
	s_addc_u32 s45, s67, 0
	s_mul_i32 s72, s65, s74
	s_add_u32 s58, s66, 0x2300
	s_mul_i32 s72, s72, s64
	s_addc_u32 s59, s67, 0
	s_mov_b32 s73, 1
	v_mov_b32_e32 v16, 0
	s_branch .LBB0_1652

.LBB0_1666:
	s_or_b64 exec, exec, s[16:17]
	v_cvt_f32_u32_e32 v4, v2
	s_waitcnt vmcnt(0)
	v_readfirstlane_b32 s14, v3
	v_sub_u32_e32 v3, 0, v2
	v_rcp_iflag_f32_e32 v4, v4
	v_add_u32_e32 v5, s14, v1
	v_mul_f32_e32 v4, 0x4f7ffffe, v4
	v_cvt_u32_f32_e32 v4, v4
	v_mul_lo_u32 v1, v3, v4
	v_mul_hi_u32 v1, v4, v1
	v_add_u32_e32 v1, v4, v1
	v_mul_hi_u32 v1, v5, v1
	v_mul_lo_u32 v3, v1, v2
	v_sub_u32_e32 v3, v5, v3
	v_add_u32_e32 v4, 1, v1
	v_cmp_ge_u32_e32 vcc, v3, v2
	s_nop 1
	v_cndmask_b32_e32 v1, v1, v4, vcc
	v_sub_u32_e32 v4, v3, v2
	v_cndmask_b32_e32 v3, v3, v4, vcc
	v_add_u32_e32 v4, 1, v1
	v_cmp_ge_u32_e32 vcc, v3, v2
	v_add_u32_e32 v3, 1, v5
	s_nop 0
	v_cndmask_b32_e32 v1, v1, v4, vcc
	v_mul_lo_u32 v4, v2, v1
	v_add_u32_e32 v2, v4, v2
	v_cmp_ne_u32_e32 vcc, v3, v2
	s_and_saveexec_b64 s[14:15], vcc
	s_xor_b64 s[14:15], exec, s[14:15]
	s_cbranch_execz .LBB0_1680
	s_cmp_lt_u32 s2, 0
	s_cbranch_scc1 .Lsb_wait_h1
	s_cmp_lg_u32 s64, 0x100
	s_cbranch_scc1 .Lsb_wait_h1
	s_cmp_lg_u32 s100, 1
	s_cbranch_scc1 .Lsb_wait_h1
	v_readfirstlane_b32 s101, v1
	s_branch .LBB0_1680

.LBB0_1700:
	s_or_b64 exec, exec, s[0:1]
	s_cmp_eq_u32 s100, 1
	s_cbranch_scc0 .Lhb_skip_3
	s_and_saveexec_b64 s[0:1], s[46:47]
	s_cbranch_execz .Lhb_done_3
	s_and_b32 s98, s2, 7
	s_lshl_b32 s98, s98, 6
	s_add_i32 s98, s98, 0x4a00
	v_mov_b32_e32 v250, s98
	v_mov_b32_e32 v251, 1
	global_atomic_add v252, v250, v251, s[66:67] sc0
	buffer_inv sc1
	s_lshr_b32 s98, s64, 3
	s_mul_i32 s98, s98, 4
	s_add_i32 s98, s98, -1
	v_add_u32_e32 v250, 0x200, v250
	s_waitcnt vmcnt(0)
	v_readfirstlane_b32 s99, v252
	s_cmp_eq_u32 s99, s98
	s_cbranch_scc0 .Lhb_wait_3
	global_atomic_add v250, v251, s[66:67]
	s_waitcnt vmcnt(0)
	s_branch .Lhb_done_3

.Lhb_skip_3:
	s_mov_b64 s[14:15], s[66:67]
	s_mov_b64 s[0:1], s[68:69]
	s_waitcnt lgkmcnt(0)
	v_mov_b32_e32 v0, v194
	s_barrier
	s_mov_b32 s42, s64
	v_mov_b32_e32 v9, v194
	v_cndmask_b32_e64 v0, 0, 1, s[56:57]
	v_cmp_ne_u32_e64 s[6:7], 1, v0
	s_andn2_b64 vcc, exec, s[56:57]
	v_readfirstlane_b32 s23, v9
	s_cbranch_vccnz .LBB0_1716
	v_lshlrev_b32_e32 v0, 4, v9
	v_add_u32_e32 v1, 0x2000, v0
	v_ashrrev_i32_e32 v2, 31, v1
	v_lshrrev_b32_e32 v2, 22, v2
	v_add_u32_e32 v2, v1, v2
	v_ashrrev_i32_e32 v8, 10, v2
	v_mul_i32_i24_e32 v2, 0x400, v8
	v_sub_u32_e32 v1, v1, v2
	v_lshrrev_b32_e32 v2, 4, v1
	v_bitop3_b32 v1, v2, v1, 32 bitop3:0x6c
	v_ashrrev_i32_e32 v2, 31, v1
	v_lshrrev_b32_e32 v2, 26, v2
	v_add_u32_e32 v2, v1, v2
	v_lshlrev_b32_e32 v3, 3, v8
	v_ashrrev_i32_e32 v10, 6, v2
	v_and_b32_e32 v3, -16, v3
	v_add_u32_e32 v3, v10, v3
	v_and_b32_e32 v4, 3, v10
	s_mov_b32 s0, 0x1fffe0
	v_lshrrev_b32_e32 v5, 2, v3
	v_lshlrev_b32_e32 v6, 1, v3
	v_and_b32_e32 v2, 0xc0, v2
	v_and_or_b32 v4, v3, s0, v4
	v_and_b32_e32 v5, 4, v5
	v_and_b32_e32 v6, 24, v6
	v_sub_u32_e32 v1, v1, v2
	v_mov_b32_e32 v2, 1
	v_or3_b32 v4, v4, v5, v6
	v_lshlrev_b32_e32 v5, 5, v8
	v_ashrrev_i16_sdwa v1, v2, sext(v1) dst_sel:DWORD dst_unused:UNUSED_PAD src0_sel:DWORD src1_sel:BYTE_0
	v_and_b32_e32 v5, 32, v5
	v_bfe_i32 v11, v1, 0, 16
	v_add_lshl_u32 v1, v5, v11, 1
	s_waitcnt vmcnt(0)
	v_lshl_add_u32 v128, v4, 11, v1
	v_lshl_add_u32 v130, v3, 11, v1
	v_bfe_i32 v1, v9, 27, 1
	v_lshrrev_b32_e32 v1, 22, v1
	v_add_u32_e32 v1, v0, v1
	v_and_b32_e32 v1, 0xfffffc00, v1
	v_sub_u32_e32 v0, v0, v1
	v_lshrrev_b32_e32 v1, 4, v0
	v_ashrrev_i32_e32 v3, 31, v9
	v_bitop3_b32 v0, v1, v0, 32 bitop3:0x6c
	v_lshrrev_b32_e32 v3, 26, v3
	v_ashrrev_i32_e32 v1, 31, v0
	v_add_u32_e32 v3, v9, v3
	v_lshrrev_b32_e32 v1, 26, v1
	v_ashrrev_i32_e32 v13, 6, v3
	s_add_u32 s43, s14, 0x3800000
	v_add_u32_e32 v1, v0, v1
	v_lshlrev_b32_e32 v3, 3, v13
	s_addc_u32 s44, s15, 0
	v_ashrrev_i32_e32 v12, 6, v1
	v_and_b32_e32 v3, -16, v3
	s_add_u32 s45, s14, 0x1180000
	v_add_u32_e32 v3, v12, v3
	v_and_b32_e32 v4, 3, v12
	s_addc_u32 s51, s15, 0
	v_and_or_b32 v4, v3, s0, v4
	s_lshr_b32 s0, s3, 29
	s_add_i32 s0, s2, s0
	s_ashr_i32 s20, s23, 6
	s_ashr_i32 s1, s0, 3
	s_and_b32 s0, s0, -8
	s_ashr_i32 s24, s23, 8
	s_lshl_b32 s56, s20, 10
	s_sub_i32 s0, s2, s0
	s_cmp_lt_i32 s0, 0
	s_movk_i32 s57, 0xb1
	s_cselect_b32 s16, s57, 0xb0
	s_mul_i32 s0, s0, s16
	s_add_i32 s0, s0, s1
	s_mul_hi_i32 s1, s0, 0x2e8ba2e9
	s_lshr_b32 s16, s1, 31
	s_ashr_i32 s1, s1, 5
	s_add_i32 s1, s1, s16
	s_lshl_b32 s16, s1, 3
	s_mulk_i32 s1, 0xb0
	s_sub_i32 s0, s0, s1
	s_sext_i32_i16 s1, s0
	s_bfe_u32 s1, s1, 0x3001c
	s_add_i32 s1, s0, s1
	s_sext_i32_i16 s17, s1
	s_and_b32 s1, s1, 0xfff8
	s_sub_i32 s0, s0, s1
	s_sext_i32_i16 s0, s0
	v_lshrrev_b32_e32 v5, 2, v3
	v_lshlrev_b32_e32 v6, 1, v3
	v_and_b32_e32 v1, 0xc0, v1
	s_lshr_b32 s22, s17, 3
	s_add_i32 s34, s16, s0
	v_and_b32_e32 v5, 4, v5
	v_and_b32_e32 v6, 24, v6
	v_sub_u32_e32 v0, v0, v1
	s_ashr_i32 s35, s34, 31
	s_bfe_i64 s[16:17], s[22:23], 0x100000
	v_or3_b32 v4, v4, v5, v6
	v_lshlrev_b32_e32 v5, 5, v13
	v_ashrrev_i16_sdwa v0, v2, sext(v0) dst_sel:DWORD dst_unused:UNUSED_PAD src0_sel:DWORD src1_sel:BYTE_0
	s_lshl_b64 s[0:1], s[34:35], 19
	s_lshl_b64 s[16:17], s[16:17], 19
	v_and_b32_e32 v5, 32, v5
	v_bfe_i32 v14, v0, 0, 16
	s_add_u32 s38, s45, s16
	v_add_lshl_u32 v0, v5, v14, 1
	s_addc_u32 s39, s51, s17
	s_add_i32 s35, s56, 0
	v_lshl_add_u32 v132, v4, 11, v0
	s_add_i32 m0, s35, 0x10000
	v_lshl_add_u32 v134, v3, 11, v0
	global_load_lds_dwordx4 v132, s[38:39]
	s_add_i32 m0, s35, 0x12000
	s_add_u32 s16, s38, 0x40000
	global_load_lds_dwordx4 v128, s[38:39]
	s_addc_u32 s17, s39, 0
	s_add_i32 m0, s35, 0x14000
	v_mov_b32_e32 v133, 0
	global_load_lds_dwordx4 v132, s[16:17]
	s_add_i32 m0, s35, 0x16000
	s_add_u32 s36, s43, s0
	s_addc_u32 s37, s44, s1
	s_add_i32 s58, s35, 0x2000
	global_load_lds_dwordx4 v128, s[16:17]
	s_mov_b32 m0, s35
	s_add_u32 s0, s36, 0x40000
	global_load_lds_dwordx4 v134, s[36:37]
	s_mov_b32 m0, s58
	s_addc_u32 s1, s37, 0
	s_add_i32 s59, s35, 0x4000
	global_load_lds_dwordx4 v130, s[36:37]
	s_mov_b32 m0, s59
	s_add_i32 s60, s35, 0x6000
	global_load_lds_dwordx4 v134, s[0:1]
	s_mov_b32 m0, s60
	v_mov_b32_e32 v129, v133
	global_load_lds_dwordx4 v130, s[0:1]
	v_mov_b32_e32 v135, v133
	v_mov_b32_e32 v131, v133
	s_cmp_eq_u32 s24, 1
	s_mov_b32 s61, 0
	v_lshl_add_u64 v[6:7], s[38:39], 0, v[132:133]
	v_lshl_add_u64 v[4:5], s[38:39], 0, v[128:129]
	v_lshl_add_u64 v[0:1], s[36:37], 0, v[134:135]
	s_cselect_b64 s[0:1], -1, 0
	s_cmp_lg_u32 s24, 1
	v_lshl_add_u64 v[2:3], s[36:37], 0, v[130:131]
	s_cbranch_scc1 .LBB0_1703
	s_barrier

.Lsb_cj_h1:
	s_barrier
	v_lshl_add_u32 v144, s34, 8, v146
	v_ashrrev_i32_e32 v145, 31, v144
	v_lshlrev_b64 v[154:155], 6, v[144:145]
	v_lshl_add_u64 v[166:167], s[18:19], 0, v[154:155]
	global_load_dwordx4 v[154:157], v[166:167], off
	global_load_dwordx4 v[158:161], v[166:167], off offset:16
	global_load_dwordx4 v[162:165], v[166:167], off offset:32
	s_nop 0
	global_load_dwordx4 v[166:169], v[166:167], off offset:48
	v_mov_b32_e32 v174, v122
	v_mov_b32_e32 v175, v114
	v_mov_b32_e32 v114, v123
	v_mov_b32_e32 v172, v124
	v_mov_b32_e32 v173, v116
	v_mov_b32_e32 v116, v125
	v_mov_b32_e32 v124, v126
	v_mov_b32_e32 v125, v118
	v_mov_b32_e32 v118, v127
	v_mov_b32_e32 v127, v112
	v_mov_b32_e32 v112, v121
	v_mov_b32_e32 v126, v120
	v_lshl_or_b32 v170, s79, 7, v148
	v_mov_b64_e32 v[120:121], s[16:17]
	v_ashrrev_i32_e32 v171, 31, v170
	s_waitcnt vmcnt(0)
	v_mov_b32_e32 v122, v155
	v_mov_b32_e32 v123, v156
	v_mov_b32_e32 v155, v157
	v_mov_b32_e32 v156, v159
	v_mov_b32_e32 v157, v160
	v_mov_b32_e32 v159, v161
	v_pk_add_f32 v[122:123], v[122:123], v[154:155]
	v_pk_add_f32 v[154:155], v[156:157], v[158:159]
	v_pk_add_f32 v[122:123], v[122:123], v[122:123] op_sel:[0,1] op_sel_hi:[1,0]
	v_pk_add_f32 v[154:155], v[154:155], v[154:155] op_sel:[0,1] op_sel_hi:[1,0]
	v_add_f32_e32 v160, v162, v163
	v_add_f32_e32 v162, v164, v165
	v_mov_b32_e32 v161, v168
	v_mov_b32_e32 v163, v169
	v_mov_b32_e32 v123, v166
	v_mov_b32_e32 v155, v167
	v_pk_add_f32 v[156:157], v[160:161], v[162:163]
	v_pk_add_f32 v[122:123], v[122:123], v[154:155]
	v_mad_i64_i32 v[154:155], s[36:37], v144, s78, v[120:121]
	v_pk_add_f32 v[122:123], v[122:123], v[156:157]
	s_nop 0
	v_add_f32_e32 v122, v122, v123
	v_fmamk_f32 v122, v122, 0x3a800000, v152
	v_mul_f32_e32 v123, 0x4b800000, v122
	v_cmp_gt_f32_e32 vcc, s73, v122
	s_nop 1
	v_cndmask_b32_e32 v122, v122, v123, vcc
	v_rsq_f32_e32 v145, v122
	v_lshlrev_b64 v[122:123], 1, v[170:171]
	v_lshl_add_u64 v[154:155], v[154:155], 0, v[122:123]
	v_mul_f32_e32 v153, 0x45800000, v145
	v_cndmask_b32_e32 v156, v145, v153, vcc
	v_pk_mul_f32 v[158:159], v[172:173], v[156:157] op_sel_hi:[1,0]
	v_pk_mul_f32 v[116:117], v[116:117], v[156:157] op_sel_hi:[1,0]
	v_pk_mul_f32 v[124:125], v[124:125], v[156:157] op_sel_hi:[1,0]
	v_pk_mul_f32 v[118:119], v[118:119], v[156:157] op_sel_hi:[1,0]
	v_pk_mul_f32 v[112:113], v[112:113], v[156:157] op_sel_hi:[1,0]
	v_pk_mul_f32 v[114:115], v[114:115], v[156:157] op_sel_hi:[1,0]
	v_mul_f32_e32 v145, 0xbfb8aa3b, v159
	v_pk_mul_f32 v[126:127], v[126:127], v[156:157] op_sel_hi:[1,0]
	v_pk_mul_f32 v[160:161], v[174:175], v[156:157] op_sel_hi:[1,0]
	v_mul_f32_e32 v153, 0xbfb8aa3b, v117
	v_mul_f32_e32 v156, 0xbfb8aa3b, v125
	v_mul_f32_e32 v157, 0xbfb8aa3b, v119
	v_mul_f32_e32 v163, 0xbfb8aa3b, v113
	v_mul_f32_e32 v165, 0xbfb8aa3b, v115
	v_exp_f32_e32 v145, v145
	v_mul_f32_e32 v162, 0xbfb8aa3b, v127
	v_mul_f32_e32 v164, 0xbfb8aa3b, v161
	v_exp_f32_e32 v153, v153
	v_exp_f32_e32 v156, v156
	v_exp_f32_e32 v157, v157
	v_exp_f32_e32 v163, v163
	v_exp_f32_e32 v165, v165
	v_exp_f32_e32 v162, v162
	v_exp_f32_e32 v164, v164
	v_add_f32_e32 v145, 1.0, v145
	v_add_f32_e32 v153, 1.0, v153
	v_add_f32_e32 v156, 1.0, v156
	v_add_f32_e32 v157, 1.0, v157
	v_add_f32_e32 v163, 1.0, v163
	v_add_f32_e32 v165, 1.0, v165
	v_rcp_f32_e32 v145, v145
	v_add_f32_e32 v162, 1.0, v162
	v_add_f32_e32 v164, 1.0, v164
	v_rcp_f32_e32 v153, v153
	v_rcp_f32_e32 v156, v156
	v_rcp_f32_e32 v157, v157
	v_rcp_f32_e32 v163, v163
	v_rcp_f32_e32 v165, v165
	v_rcp_f32_e32 v162, v162
	v_rcp_f32_e32 v164, v164
	v_mul_f32_e32 v145, v159, v145
	v_mul_f32_e32 v117, v117, v153
	v_mul_f32_e32 v125, v125, v156
	v_mul_f32_e32 v119, v119, v157
	v_mul_f32_e32 v113, v113, v163
	v_mul_f32_e32 v115, v115, v165
	v_mul_f32_e32 v145, v158, v145
	v_or_b32_e32 v158, 16, v144
	v_mul_f32_e32 v127, v127, v162
	v_mul_f32_e32 v153, v161, v164
	v_mul_f32_e32 v116, v116, v117
	v_mul_f32_e32 v117, v124, v125
	v_mul_f32_e32 v118, v118, v119
	v_mul_f32_e32 v124, v112, v113
	v_mul_f32_e32 v115, v114, v115
	v_cvt_pk_bf16_f32 v112, v145, v116
	v_cvt_pk_bf16_f32 v113, v117, v118
	v_ashrrev_i32_e32 v159, 31, v158
	v_mul_f32_e32 v119, v126, v127
	v_mul_f32_e32 v125, v160, v153
	v_cvt_pk_bf16_f32 v114, v119, v124
	v_cvt_pk_bf16_f32 v115, v125, v115
	global_store_dwordx4 v[154:155], v[112:115], off
	v_mov_b32_e32 v160, v108
	v_mov_b32_e32 v161, v100
	v_lshlrev_b64 v[112:113], 6, v[158:159]
	v_lshl_add_u64 v[154:155], s[18:19], 0, v[112:113]
	global_load_dwordx4 v[112:115], v[154:155], off
	global_load_dwordx4 v[116:119], v[154:155], off offset:16
	global_load_dwordx4 v[124:127], v[154:155], off offset:32
	s_nop 0
	global_load_dwordx4 v[154:157], v[154:155], off offset:48
	v_mov_b32_e32 v100, v109
	v_mov_b32_e32 v108, v110
	v_mov_b32_e32 v109, v102
	v_mov_b32_e32 v102, v111
	v_mov_b32_e32 v110, v104
	v_mov_b32_e32 v111, v96
	v_mov_b32_e32 v96, v105
	v_mov_b32_e32 v104, v106
	v_mov_b32_e32 v105, v98
	v_mov_b32_e32 v98, v107
	s_waitcnt vmcnt(3)
	v_mov_b32_e32 v106, v113
	v_mov_b32_e32 v107, v114
	v_mov_b32_e32 v113, v115
	s_waitcnt vmcnt(2)
	v_mov_b32_e32 v114, v117
	v_mov_b32_e32 v115, v118
	v_mov_b32_e32 v117, v119
	v_pk_add_f32 v[106:107], v[106:107], v[112:113]
	v_pk_add_f32 v[112:113], v[114:115], v[116:117]
	v_pk_add_f32 v[106:107], v[106:107], v[106:107] op_sel:[0,1] op_sel_hi:[1,0]
	v_pk_add_f32 v[112:113], v[112:113], v[112:113] op_sel:[0,1] op_sel_hi:[1,0]
	s_waitcnt vmcnt(1)
	v_add_f32_e32 v118, v124, v125
	v_add_f32_e32 v124, v126, v127
	s_waitcnt vmcnt(0)
	v_mov_b32_e32 v119, v156
	v_mov_b32_e32 v125, v157
	v_mov_b32_e32 v107, v154
	v_mov_b32_e32 v113, v155
	v_pk_add_f32 v[114:115], v[118:119], v[124:125]
	v_pk_add_f32 v[106:107], v[106:107], v[112:113]
	s_nop 0
	v_pk_add_f32 v[106:107], v[106:107], v[114:115]
	s_nop 0
	v_add_f32_e32 v106, v106, v107
	v_fmamk_f32 v106, v106, 0x3a800000, v152
	v_mul_f32_e32 v107, 0x4b800000, v106
	v_cmp_gt_f32_e32 vcc, s73, v106
	s_nop 1
	v_cndmask_b32_e32 v106, v106, v107, vcc
	v_rsq_f32_e32 v112, v106
	v_mad_i64_i32 v[106:107], s[36:37], v158, s78, v[120:121]
	v_lshl_add_u64 v[106:107], v[106:107], 0, v[122:123]
	v_mul_f32_e32 v113, 0x45800000, v112
	v_cndmask_b32_e32 v112, v112, v113, vcc
	v_pk_mul_f32 v[114:115], v[160:161], v[112:113] op_sel_hi:[1,0]
	v_pk_mul_f32 v[100:101], v[100:101], v[112:113] op_sel_hi:[1,0]
	v_pk_mul_f32 v[108:109], v[108:109], v[112:113] op_sel_hi:[1,0]
	v_pk_mul_f32 v[102:103], v[102:103], v[112:113] op_sel_hi:[1,0]
	v_pk_mul_f32 v[110:111], v[110:111], v[112:113] op_sel_hi:[1,0]
	v_pk_mul_f32 v[96:97], v[96:97], v[112:113] op_sel_hi:[1,0]
	v_pk_mul_f32 v[104:105], v[104:105], v[112:113] op_sel_hi:[1,0]
	v_pk_mul_f32 v[98:99], v[98:99], v[112:113] op_sel_hi:[1,0]
	v_mul_f32_e32 v112, 0xbfb8aa3b, v115
	v_mul_f32_e32 v113, 0xbfb8aa3b, v101
	v_mul_f32_e32 v116, 0xbfb8aa3b, v109
	v_mul_f32_e32 v119, 0xbfb8aa3b, v97
	v_exp_f32_e32 v112, v112
	v_mul_f32_e32 v117, 0xbfb8aa3b, v103
	v_mul_f32_e32 v125, 0xbfb8aa3b, v99
	v_exp_f32_e32 v113, v113
	v_exp_f32_e32 v116, v116
	v_exp_f32_e32 v119, v119
	v_mul_f32_e32 v118, 0xbfb8aa3b, v111
	v_mul_f32_e32 v124, 0xbfb8aa3b, v105
	v_exp_f32_e32 v117, v117
	v_exp_f32_e32 v125, v125
	v_exp_f32_e32 v118, v118
	v_exp_f32_e32 v124, v124
	v_add_f32_e32 v112, 1.0, v112
	v_add_f32_e32 v113, 1.0, v113
	v_add_f32_e32 v116, 1.0, v116
	v_add_f32_e32 v119, 1.0, v119
	v_rcp_f32_e32 v112, v112
	v_add_f32_e32 v117, 1.0, v117
	v_add_f32_e32 v125, 1.0, v125
	v_rcp_f32_e32 v113, v113
	v_rcp_f32_e32 v116, v116
	v_rcp_f32_e32 v119, v119
	v_add_f32_e32 v118, 1.0, v118
	v_add_f32_e32 v124, 1.0, v124
	v_rcp_f32_e32 v117, v117
	v_rcp_f32_e32 v125, v125
	v_rcp_f32_e32 v118, v118
	v_rcp_f32_e32 v124, v124
	v_mul_f32_e32 v112, v115, v112
	v_mul_f32_e32 v101, v101, v113
	v_mul_f32_e32 v109, v109, v116
	v_mul_f32_e32 v97, v97, v119
	v_mul_f32_e32 v112, v114, v112
	v_mul_f32_e32 v103, v103, v117
	v_mul_f32_e32 v99, v99, v125
	v_mul_f32_e32 v100, v100, v101
	v_mul_f32_e32 v101, v108, v109
	v_mul_f32_e32 v108, v96, v97
	v_cvt_pk_bf16_f32 v96, v112, v100
	v_or_b32_e32 v112, 32, v144
	v_mul_f32_e32 v111, v111, v118
	v_mul_f32_e32 v105, v105, v124
	v_mul_f32_e32 v102, v102, v103
	v_mul_f32_e32 v99, v98, v99
	v_cvt_pk_bf16_f32 v97, v101, v102
	v_ashrrev_i32_e32 v113, 31, v112
	v_mul_f32_e32 v103, v110, v111
	v_mul_f32_e32 v104, v104, v105
	v_cvt_pk_bf16_f32 v98, v103, v108
	v_cvt_pk_bf16_f32 v99, v104, v99
	global_store_dwordx4 v[106:107], v[96:99], off
	v_mov_b32_e32 v114, v92
	v_mov_b32_e32 v115, v84
	v_lshlrev_b64 v[96:97], 6, v[112:113]
	v_lshl_add_u64 v[108:109], s[18:19], 0, v[96:97]
	global_load_dwordx4 v[96:99], v[108:109], off
	global_load_dwordx4 v[100:103], v[108:109], off offset:16
	global_load_dwordx4 v[104:107], v[108:109], off offset:32
	s_nop 0
	global_load_dwordx4 v[108:111], v[108:109], off offset:48
	v_mov_b32_e32 v84, v93
	v_mov_b32_e32 v92, v94
	v_mov_b32_e32 v93, v86
	v_mov_b32_e32 v86, v95
	v_mov_b32_e32 v94, v88
	v_mov_b32_e32 v95, v80
	v_mov_b32_e32 v80, v89
	v_mov_b32_e32 v88, v90
	v_mov_b32_e32 v89, v82
	v_mov_b32_e32 v82, v91
	s_waitcnt vmcnt(3)
	v_mov_b32_e32 v90, v97
	v_mov_b32_e32 v91, v98
	v_mov_b32_e32 v97, v99
	s_waitcnt vmcnt(2)
	v_mov_b32_e32 v98, v101
	v_mov_b32_e32 v99, v102
	v_mov_b32_e32 v101, v103
	v_pk_add_f32 v[90:91], v[90:91], v[96:97]
	v_pk_add_f32 v[96:97], v[98:99], v[100:101]
	v_pk_add_f32 v[90:91], v[90:91], v[90:91] op_sel:[0,1] op_sel_hi:[1,0]
	v_pk_add_f32 v[96:97], v[96:97], v[96:97] op_sel:[0,1] op_sel_hi:[1,0]
	s_waitcnt vmcnt(1)
	v_add_f32_e32 v102, v104, v105
	v_add_f32_e32 v104, v106, v107
	s_waitcnt vmcnt(0)
	v_mov_b32_e32 v103, v110
	v_mov_b32_e32 v105, v111
	v_mov_b32_e32 v91, v108
	v_mov_b32_e32 v97, v109
	v_pk_add_f32 v[98:99], v[102:103], v[104:105]
	v_pk_add_f32 v[90:91], v[90:91], v[96:97]
	s_nop 0
	v_pk_add_f32 v[90:91], v[90:91], v[98:99]
	s_nop 0
	v_add_f32_e32 v90, v90, v91
	v_fmamk_f32 v90, v90, 0x3a800000, v152
	v_mul_f32_e32 v91, 0x4b800000, v90
	v_cmp_gt_f32_e32 vcc, s73, v90
	s_nop 1
	v_cndmask_b32_e32 v90, v90, v91, vcc
	v_rsq_f32_e32 v96, v90
	v_mad_i64_i32 v[90:91], s[36:37], v112, s78, v[120:121]
	v_lshl_add_u64 v[90:91], v[90:91], 0, v[122:123]
	v_mul_f32_e32 v97, 0x45800000, v96
	v_cndmask_b32_e32 v96, v96, v97, vcc
	v_pk_mul_f32 v[98:99], v[114:115], v[96:97] op_sel_hi:[1,0]
	v_pk_mul_f32 v[84:85], v[84:85], v[96:97] op_sel_hi:[1,0]
	v_pk_mul_f32 v[92:93], v[92:93], v[96:97] op_sel_hi:[1,0]
	v_pk_mul_f32 v[86:87], v[86:87], v[96:97] op_sel_hi:[1,0]
	v_pk_mul_f32 v[94:95], v[94:95], v[96:97] op_sel_hi:[1,0]
	v_pk_mul_f32 v[80:81], v[80:81], v[96:97] op_sel_hi:[1,0]
	v_pk_mul_f32 v[88:89], v[88:89], v[96:97] op_sel_hi:[1,0]
	v_pk_mul_f32 v[82:83], v[82:83], v[96:97] op_sel_hi:[1,0]
	v_mul_f32_e32 v96, 0xbfb8aa3b, v99
	v_mul_f32_e32 v97, 0xbfb8aa3b, v85
	v_mul_f32_e32 v100, 0xbfb8aa3b, v93
	v_mul_f32_e32 v103, 0xbfb8aa3b, v81
	v_exp_f32_e32 v96, v96
	v_mul_f32_e32 v101, 0xbfb8aa3b, v87
	v_mul_f32_e32 v105, 0xbfb8aa3b, v83
	v_exp_f32_e32 v97, v97
	v_exp_f32_e32 v100, v100
	v_exp_f32_e32 v103, v103
	v_mul_f32_e32 v102, 0xbfb8aa3b, v95
	v_mul_f32_e32 v104, 0xbfb8aa3b, v89
	v_exp_f32_e32 v101, v101
	v_exp_f32_e32 v105, v105
	v_exp_f32_e32 v102, v102
	v_exp_f32_e32 v104, v104
	v_add_f32_e32 v96, 1.0, v96
	v_add_f32_e32 v97, 1.0, v97
	v_add_f32_e32 v100, 1.0, v100
	v_add_f32_e32 v103, 1.0, v103
	v_rcp_f32_e32 v96, v96
	v_add_f32_e32 v101, 1.0, v101
	v_add_f32_e32 v105, 1.0, v105
	v_rcp_f32_e32 v97, v97
	v_rcp_f32_e32 v100, v100
	v_rcp_f32_e32 v103, v103
	v_add_f32_e32 v102, 1.0, v102
	v_add_f32_e32 v104, 1.0, v104
	v_rcp_f32_e32 v101, v101
	v_rcp_f32_e32 v105, v105
	v_rcp_f32_e32 v102, v102
	v_rcp_f32_e32 v104, v104
	v_mul_f32_e32 v96, v99, v96
	v_mul_f32_e32 v85, v85, v97
	v_mul_f32_e32 v93, v93, v100
	v_mul_f32_e32 v81, v81, v103
	v_mul_f32_e32 v96, v98, v96
	v_mul_f32_e32 v87, v87, v101
	v_mul_f32_e32 v83, v83, v105
	v_mul_f32_e32 v84, v84, v85
	v_mul_f32_e32 v85, v92, v93
	v_mul_f32_e32 v92, v80, v81
	v_cvt_pk_bf16_f32 v80, v96, v84
	v_or_b32_e32 v96, 48, v144
	v_mul_f32_e32 v95, v95, v102
	v_mul_f32_e32 v89, v89, v104
	v_mul_f32_e32 v86, v86, v87
	v_mul_f32_e32 v83, v82, v83
	v_cvt_pk_bf16_f32 v81, v85, v86
	v_ashrrev_i32_e32 v97, 31, v96
	v_mul_f32_e32 v87, v94, v95
	v_mul_f32_e32 v88, v88, v89
	v_cvt_pk_bf16_f32 v82, v87, v92
	v_cvt_pk_bf16_f32 v83, v88, v83
	global_store_dwordx4 v[90:91], v[80:83], off
	v_mov_b32_e32 v98, v76
	v_mov_b32_e32 v99, v68
	v_lshlrev_b64 v[80:81], 6, v[96:97]
	v_lshl_add_u64 v[92:93], s[18:19], 0, v[80:81]
	global_load_dwordx4 v[80:83], v[92:93], off
	global_load_dwordx4 v[84:87], v[92:93], off offset:16
	global_load_dwordx4 v[88:91], v[92:93], off offset:32
	s_nop 0
	global_load_dwordx4 v[92:95], v[92:93], off offset:48
	v_mov_b32_e32 v68, v77
	v_mov_b32_e32 v76, v78
	v_mov_b32_e32 v77, v70
	v_mov_b32_e32 v70, v79
	v_mov_b32_e32 v78, v72
	v_mov_b32_e32 v79, v64
	v_mov_b32_e32 v64, v73
	v_mov_b32_e32 v72, v74
	v_mov_b32_e32 v73, v66
	v_mov_b32_e32 v66, v75
	s_waitcnt vmcnt(3)
	v_mov_b32_e32 v74, v81
	v_mov_b32_e32 v75, v82
	v_mov_b32_e32 v81, v83
	s_waitcnt vmcnt(2)
	v_mov_b32_e32 v82, v85
	v_mov_b32_e32 v83, v86
	v_mov_b32_e32 v85, v87
	v_pk_add_f32 v[74:75], v[74:75], v[80:81]
	v_pk_add_f32 v[80:81], v[82:83], v[84:85]
	v_pk_add_f32 v[74:75], v[74:75], v[74:75] op_sel:[0,1] op_sel_hi:[1,0]
	v_pk_add_f32 v[80:81], v[80:81], v[80:81] op_sel:[0,1] op_sel_hi:[1,0]
	s_waitcnt vmcnt(1)
	v_add_f32_e32 v86, v88, v89
	v_add_f32_e32 v88, v90, v91
	s_waitcnt vmcnt(0)
	v_mov_b32_e32 v87, v94
	v_mov_b32_e32 v89, v95
	v_mov_b32_e32 v75, v92
	v_mov_b32_e32 v81, v93
	v_pk_add_f32 v[82:83], v[86:87], v[88:89]
	v_pk_add_f32 v[74:75], v[74:75], v[80:81]
	s_nop 0
	v_pk_add_f32 v[74:75], v[74:75], v[82:83]
	s_nop 0
	v_add_f32_e32 v74, v74, v75
	v_fmamk_f32 v74, v74, 0x3a800000, v152
	v_mul_f32_e32 v75, 0x4b800000, v74
	v_cmp_gt_f32_e32 vcc, s73, v74
	s_nop 1
	v_cndmask_b32_e32 v74, v74, v75, vcc
	v_rsq_f32_e32 v80, v74
	v_mad_i64_i32 v[74:75], s[36:37], v96, s78, v[120:121]
	v_lshl_add_u64 v[74:75], v[74:75], 0, v[122:123]
	v_mul_f32_e32 v81, 0x45800000, v80
	v_cndmask_b32_e32 v80, v80, v81, vcc
	v_pk_mul_f32 v[82:83], v[98:99], v[80:81] op_sel_hi:[1,0]
	v_pk_mul_f32 v[68:69], v[68:69], v[80:81] op_sel_hi:[1,0]
	v_pk_mul_f32 v[76:77], v[76:77], v[80:81] op_sel_hi:[1,0]
	v_pk_mul_f32 v[70:71], v[70:71], v[80:81] op_sel_hi:[1,0]
	v_pk_mul_f32 v[78:79], v[78:79], v[80:81] op_sel_hi:[1,0]
	v_pk_mul_f32 v[64:65], v[64:65], v[80:81] op_sel_hi:[1,0]
	v_pk_mul_f32 v[72:73], v[72:73], v[80:81] op_sel_hi:[1,0]
	v_pk_mul_f32 v[66:67], v[66:67], v[80:81] op_sel_hi:[1,0]
	v_mul_f32_e32 v80, 0xbfb8aa3b, v83
	v_mul_f32_e32 v81, 0xbfb8aa3b, v69
	v_mul_f32_e32 v84, 0xbfb8aa3b, v77
	v_mul_f32_e32 v87, 0xbfb8aa3b, v65
	v_exp_f32_e32 v80, v80
	v_mul_f32_e32 v85, 0xbfb8aa3b, v71
	v_mul_f32_e32 v89, 0xbfb8aa3b, v67
	v_exp_f32_e32 v81, v81
	v_exp_f32_e32 v84, v84
	v_exp_f32_e32 v87, v87
	v_mul_f32_e32 v86, 0xbfb8aa3b, v79
	v_mul_f32_e32 v88, 0xbfb8aa3b, v73
	v_exp_f32_e32 v85, v85
	v_exp_f32_e32 v89, v89
	v_exp_f32_e32 v86, v86
	v_exp_f32_e32 v88, v88
	v_add_f32_e32 v80, 1.0, v80
	v_add_f32_e32 v81, 1.0, v81
	v_add_f32_e32 v84, 1.0, v84
	v_add_f32_e32 v87, 1.0, v87
	v_rcp_f32_e32 v80, v80
	v_add_f32_e32 v85, 1.0, v85
	v_add_f32_e32 v89, 1.0, v89
	v_rcp_f32_e32 v81, v81
	v_rcp_f32_e32 v84, v84
	v_rcp_f32_e32 v87, v87
	v_add_f32_e32 v86, 1.0, v86
	v_add_f32_e32 v88, 1.0, v88
	v_rcp_f32_e32 v85, v85
	v_rcp_f32_e32 v89, v89
	v_rcp_f32_e32 v86, v86
	v_rcp_f32_e32 v88, v88
	v_mul_f32_e32 v80, v83, v80
	v_mul_f32_e32 v69, v69, v81
	v_mul_f32_e32 v77, v77, v84
	v_mul_f32_e32 v65, v65, v87
	v_mul_f32_e32 v80, v82, v80
	v_mul_f32_e32 v71, v71, v85
	v_mul_f32_e32 v67, v67, v89
	v_mul_f32_e32 v68, v68, v69
	v_mul_f32_e32 v69, v76, v77
	v_mul_f32_e32 v76, v64, v65
	v_cvt_pk_bf16_f32 v64, v80, v68
	v_add_u32_e32 v80, 0x80, v144
	v_mul_f32_e32 v79, v79, v86
	v_mul_f32_e32 v73, v73, v88
	v_mul_f32_e32 v70, v70, v71
	v_mul_f32_e32 v67, v66, v67
	v_cvt_pk_bf16_f32 v65, v69, v70
	v_ashrrev_i32_e32 v81, 31, v80
	v_mul_f32_e32 v71, v78, v79
	v_mul_f32_e32 v72, v72, v73
	v_cvt_pk_bf16_f32 v66, v71, v76
	v_cvt_pk_bf16_f32 v67, v72, v67
	global_store_dwordx4 v[74:75], v[64:67], off
	v_mov_b32_e32 v82, v60
	v_mov_b32_e32 v83, v52
	v_lshlrev_b64 v[64:65], 6, v[80:81]
	v_lshl_add_u64 v[76:77], s[18:19], 0, v[64:65]
	global_load_dwordx4 v[64:67], v[76:77], off
	global_load_dwordx4 v[68:71], v[76:77], off offset:16
	global_load_dwordx4 v[72:75], v[76:77], off offset:32
	s_nop 0
	global_load_dwordx4 v[76:79], v[76:77], off offset:48
	v_mov_b32_e32 v52, v61
	v_mov_b32_e32 v60, v62
	v_mov_b32_e32 v61, v54
	v_mov_b32_e32 v54, v63
	v_mov_b32_e32 v62, v56
	v_mov_b32_e32 v63, v48
	v_mov_b32_e32 v48, v57
	v_mov_b32_e32 v56, v58
	v_mov_b32_e32 v57, v50
	v_mov_b32_e32 v50, v59
	s_waitcnt vmcnt(3)
	v_mov_b32_e32 v58, v65
	v_mov_b32_e32 v59, v66
	v_mov_b32_e32 v65, v67
	s_waitcnt vmcnt(2)
	v_mov_b32_e32 v66, v69
	v_mov_b32_e32 v67, v70
	v_mov_b32_e32 v69, v71
	v_pk_add_f32 v[58:59], v[58:59], v[64:65]
	v_pk_add_f32 v[64:65], v[66:67], v[68:69]
	v_pk_add_f32 v[58:59], v[58:59], v[58:59] op_sel:[0,1] op_sel_hi:[1,0]
	v_pk_add_f32 v[64:65], v[64:65], v[64:65] op_sel:[0,1] op_sel_hi:[1,0]
	s_waitcnt vmcnt(1)
	v_add_f32_e32 v70, v72, v73
	v_add_f32_e32 v72, v74, v75
	s_waitcnt vmcnt(0)
	v_mov_b32_e32 v71, v78
	v_mov_b32_e32 v73, v79
	v_mov_b32_e32 v59, v76
	v_mov_b32_e32 v65, v77
	v_pk_add_f32 v[66:67], v[70:71], v[72:73]
	v_pk_add_f32 v[58:59], v[58:59], v[64:65]
	s_nop 0
	v_pk_add_f32 v[58:59], v[58:59], v[66:67]
	s_nop 0
	v_add_f32_e32 v58, v58, v59
	v_fmamk_f32 v58, v58, 0x3a800000, v152
	v_mul_f32_e32 v59, 0x4b800000, v58
	v_cmp_gt_f32_e32 vcc, s73, v58
	s_nop 1
	v_cndmask_b32_e32 v58, v58, v59, vcc
	v_rsq_f32_e32 v64, v58
	v_mad_i64_i32 v[58:59], s[36:37], v80, s78, v[120:121]
	v_lshl_add_u64 v[58:59], v[58:59], 0, v[122:123]
	v_mul_f32_e32 v65, 0x45800000, v64
	v_cndmask_b32_e32 v64, v64, v65, vcc
	v_pk_mul_f32 v[66:67], v[82:83], v[64:65] op_sel_hi:[1,0]
	v_pk_mul_f32 v[52:53], v[52:53], v[64:65] op_sel_hi:[1,0]
	v_pk_mul_f32 v[60:61], v[60:61], v[64:65] op_sel_hi:[1,0]
	v_pk_mul_f32 v[54:55], v[54:55], v[64:65] op_sel_hi:[1,0]
	v_pk_mul_f32 v[62:63], v[62:63], v[64:65] op_sel_hi:[1,0]
	v_pk_mul_f32 v[48:49], v[48:49], v[64:65] op_sel_hi:[1,0]
	v_pk_mul_f32 v[56:57], v[56:57], v[64:65] op_sel_hi:[1,0]
	v_pk_mul_f32 v[50:51], v[50:51], v[64:65] op_sel_hi:[1,0]
	v_mul_f32_e32 v64, 0xbfb8aa3b, v67
	v_mul_f32_e32 v65, 0xbfb8aa3b, v53
	v_mul_f32_e32 v68, 0xbfb8aa3b, v61
	v_mul_f32_e32 v71, 0xbfb8aa3b, v49
	v_exp_f32_e32 v64, v64
	v_mul_f32_e32 v69, 0xbfb8aa3b, v55
	v_mul_f32_e32 v73, 0xbfb8aa3b, v51
	v_exp_f32_e32 v65, v65
	v_exp_f32_e32 v68, v68
	v_exp_f32_e32 v71, v71
	v_mul_f32_e32 v70, 0xbfb8aa3b, v63
	v_mul_f32_e32 v72, 0xbfb8aa3b, v57
	v_exp_f32_e32 v69, v69
	v_exp_f32_e32 v73, v73
	v_exp_f32_e32 v70, v70
	v_exp_f32_e32 v72, v72
	v_add_f32_e32 v64, 1.0, v64
	v_add_f32_e32 v65, 1.0, v65
	v_add_f32_e32 v68, 1.0, v68
	v_add_f32_e32 v71, 1.0, v71
	v_rcp_f32_e32 v64, v64
	v_add_f32_e32 v69, 1.0, v69
	v_add_f32_e32 v73, 1.0, v73
	v_rcp_f32_e32 v65, v65
	v_rcp_f32_e32 v68, v68
	v_rcp_f32_e32 v71, v71
	v_add_f32_e32 v70, 1.0, v70
	v_add_f32_e32 v72, 1.0, v72
	v_rcp_f32_e32 v69, v69
	v_rcp_f32_e32 v73, v73
	v_rcp_f32_e32 v70, v70
	v_rcp_f32_e32 v72, v72
	v_mul_f32_e32 v64, v67, v64
	v_mul_f32_e32 v53, v53, v65
	v_mul_f32_e32 v61, v61, v68
	v_mul_f32_e32 v49, v49, v71
	v_mul_f32_e32 v64, v66, v64
	v_mul_f32_e32 v55, v55, v69
	v_mul_f32_e32 v51, v51, v73
	v_mul_f32_e32 v52, v52, v53
	v_mul_f32_e32 v53, v60, v61
	v_mul_f32_e32 v60, v48, v49
	v_cvt_pk_bf16_f32 v48, v64, v52
	v_add_u32_e32 v64, 0x90, v144
	v_mul_f32_e32 v63, v63, v70
	v_mul_f32_e32 v57, v57, v72
	v_mul_f32_e32 v54, v54, v55
	v_mul_f32_e32 v51, v50, v51
	v_cvt_pk_bf16_f32 v49, v53, v54
	v_ashrrev_i32_e32 v65, 31, v64
	v_mul_f32_e32 v55, v62, v63
	v_mul_f32_e32 v56, v56, v57
	v_cvt_pk_bf16_f32 v50, v55, v60
	v_cvt_pk_bf16_f32 v51, v56, v51
	global_store_dwordx4 v[58:59], v[48:51], off
	v_mov_b32_e32 v66, v44
	v_mov_b32_e32 v67, v36
	v_lshlrev_b64 v[48:49], 6, v[64:65]
	v_lshl_add_u64 v[60:61], s[18:19], 0, v[48:49]
	global_load_dwordx4 v[48:51], v[60:61], off
	global_load_dwordx4 v[52:55], v[60:61], off offset:16
	global_load_dwordx4 v[56:59], v[60:61], off offset:32
	s_nop 0
	global_load_dwordx4 v[60:63], v[60:61], off offset:48
	v_mov_b32_e32 v36, v45
	v_mov_b32_e32 v44, v46
	v_mov_b32_e32 v45, v38
	v_mov_b32_e32 v38, v47
	v_mov_b32_e32 v46, v40
	v_mov_b32_e32 v47, v32
	v_mov_b32_e32 v32, v41
	v_mov_b32_e32 v40, v42
	v_mov_b32_e32 v41, v34
	v_mov_b32_e32 v34, v43
	s_waitcnt vmcnt(3)
	v_mov_b32_e32 v42, v49
	v_mov_b32_e32 v43, v50
	v_mov_b32_e32 v49, v51
	s_waitcnt vmcnt(2)
	v_mov_b32_e32 v50, v53
	v_mov_b32_e32 v51, v54
	v_mov_b32_e32 v53, v55
	v_pk_add_f32 v[42:43], v[42:43], v[48:49]
	v_pk_add_f32 v[48:49], v[50:51], v[52:53]
	v_pk_add_f32 v[42:43], v[42:43], v[42:43] op_sel:[0,1] op_sel_hi:[1,0]
	v_pk_add_f32 v[48:49], v[48:49], v[48:49] op_sel:[0,1] op_sel_hi:[1,0]
	s_waitcnt vmcnt(1)
	v_add_f32_e32 v54, v56, v57
	v_add_f32_e32 v56, v58, v59
	s_waitcnt vmcnt(0)
	v_mov_b32_e32 v55, v62
	v_mov_b32_e32 v57, v63
	v_mov_b32_e32 v43, v60
	v_mov_b32_e32 v49, v61
	v_pk_add_f32 v[50:51], v[54:55], v[56:57]
	v_pk_add_f32 v[42:43], v[42:43], v[48:49]
	s_nop 0
	v_pk_add_f32 v[42:43], v[42:43], v[50:51]
	s_nop 0
	v_add_f32_e32 v42, v42, v43
	v_fmamk_f32 v42, v42, 0x3a800000, v152
	v_mul_f32_e32 v43, 0x4b800000, v42
	v_cmp_gt_f32_e32 vcc, s73, v42
	s_nop 1
	v_cndmask_b32_e32 v42, v42, v43, vcc
	v_rsq_f32_e32 v48, v42
	v_mad_i64_i32 v[42:43], s[36:37], v64, s78, v[120:121]
	v_lshl_add_u64 v[42:43], v[42:43], 0, v[122:123]
	v_mul_f32_e32 v49, 0x45800000, v48
	v_cndmask_b32_e32 v48, v48, v49, vcc
	v_pk_mul_f32 v[50:51], v[66:67], v[48:49] op_sel_hi:[1,0]
	v_pk_mul_f32 v[36:37], v[36:37], v[48:49] op_sel_hi:[1,0]
	v_pk_mul_f32 v[44:45], v[44:45], v[48:49] op_sel_hi:[1,0]
	v_pk_mul_f32 v[38:39], v[38:39], v[48:49] op_sel_hi:[1,0]
	v_pk_mul_f32 v[46:47], v[46:47], v[48:49] op_sel_hi:[1,0]
	v_pk_mul_f32 v[32:33], v[32:33], v[48:49] op_sel_hi:[1,0]
	v_pk_mul_f32 v[40:41], v[40:41], v[48:49] op_sel_hi:[1,0]
	v_pk_mul_f32 v[34:35], v[34:35], v[48:49] op_sel_hi:[1,0]
	v_mul_f32_e32 v48, 0xbfb8aa3b, v51
	v_mul_f32_e32 v49, 0xbfb8aa3b, v37
	v_mul_f32_e32 v52, 0xbfb8aa3b, v45
	v_mul_f32_e32 v55, 0xbfb8aa3b, v33
	v_exp_f32_e32 v48, v48
	v_mul_f32_e32 v53, 0xbfb8aa3b, v39
	v_mul_f32_e32 v57, 0xbfb8aa3b, v35
	v_exp_f32_e32 v49, v49
	v_exp_f32_e32 v52, v52
	v_exp_f32_e32 v55, v55
	v_mul_f32_e32 v54, 0xbfb8aa3b, v47
	v_mul_f32_e32 v56, 0xbfb8aa3b, v41
	v_exp_f32_e32 v53, v53
	v_exp_f32_e32 v57, v57
	v_exp_f32_e32 v54, v54
	v_exp_f32_e32 v56, v56
	v_add_f32_e32 v48, 1.0, v48
	v_add_f32_e32 v49, 1.0, v49
	v_add_f32_e32 v52, 1.0, v52
	v_add_f32_e32 v55, 1.0, v55
	v_rcp_f32_e32 v48, v48
	v_add_f32_e32 v53, 1.0, v53
	v_add_f32_e32 v57, 1.0, v57
	v_rcp_f32_e32 v49, v49
	v_rcp_f32_e32 v52, v52
	v_rcp_f32_e32 v55, v55
	v_add_f32_e32 v54, 1.0, v54
	v_add_f32_e32 v56, 1.0, v56
	v_rcp_f32_e32 v53, v53
	v_rcp_f32_e32 v57, v57
	v_rcp_f32_e32 v54, v54
	v_rcp_f32_e32 v56, v56
	v_mul_f32_e32 v48, v51, v48
	v_mul_f32_e32 v37, v37, v49
	v_mul_f32_e32 v45, v45, v52
	v_mul_f32_e32 v33, v33, v55
	v_mul_f32_e32 v48, v50, v48
	v_mul_f32_e32 v39, v39, v53
	v_mul_f32_e32 v35, v35, v57
	v_mul_f32_e32 v36, v36, v37
	v_mul_f32_e32 v37, v44, v45
	v_mul_f32_e32 v44, v32, v33
	v_cvt_pk_bf16_f32 v32, v48, v36
	v_add_u32_e32 v48, 0xa0, v144
	v_mul_f32_e32 v47, v47, v54
	v_mul_f32_e32 v41, v41, v56
	v_mul_f32_e32 v38, v38, v39
	v_mul_f32_e32 v35, v34, v35
	v_cvt_pk_bf16_f32 v33, v37, v38
	v_ashrrev_i32_e32 v49, 31, v48
	v_mul_f32_e32 v39, v46, v47
	v_mul_f32_e32 v40, v40, v41
	v_cvt_pk_bf16_f32 v34, v39, v44
	v_cvt_pk_bf16_f32 v35, v40, v35
	global_store_dwordx4 v[42:43], v[32:35], off
	v_mov_b32_e32 v50, v28
	v_mov_b32_e32 v51, v20
	v_lshlrev_b64 v[32:33], 6, v[48:49]
	v_lshl_add_u64 v[44:45], s[18:19], 0, v[32:33]
	global_load_dwordx4 v[32:35], v[44:45], off
	global_load_dwordx4 v[36:39], v[44:45], off offset:16
	global_load_dwordx4 v[40:43], v[44:45], off offset:32
	s_nop 0
	global_load_dwordx4 v[44:47], v[44:45], off offset:48
	v_mov_b32_e32 v20, v29
	v_mov_b32_e32 v28, v30
	v_mov_b32_e32 v29, v22
	v_mov_b32_e32 v22, v31
	v_mov_b32_e32 v30, v24
	v_mov_b32_e32 v31, v16
	v_mov_b32_e32 v16, v25
	v_mov_b32_e32 v24, v26
	v_mov_b32_e32 v25, v18
	v_mov_b32_e32 v18, v27
	s_waitcnt vmcnt(3)
	v_mov_b32_e32 v26, v33
	v_mov_b32_e32 v27, v34
	v_mov_b32_e32 v33, v35
	s_waitcnt vmcnt(2)
	v_mov_b32_e32 v34, v37
	v_mov_b32_e32 v35, v38
	v_mov_b32_e32 v37, v39
	v_pk_add_f32 v[26:27], v[26:27], v[32:33]
	v_pk_add_f32 v[32:33], v[34:35], v[36:37]
	v_pk_add_f32 v[26:27], v[26:27], v[26:27] op_sel:[0,1] op_sel_hi:[1,0]
	v_pk_add_f32 v[32:33], v[32:33], v[32:33] op_sel:[0,1] op_sel_hi:[1,0]
	s_waitcnt vmcnt(1)
	v_add_f32_e32 v38, v40, v41
	v_add_f32_e32 v40, v42, v43
	s_waitcnt vmcnt(0)
	v_mov_b32_e32 v39, v46
	v_mov_b32_e32 v41, v47
	v_mov_b32_e32 v27, v44
	v_mov_b32_e32 v33, v45
	v_pk_add_f32 v[34:35], v[38:39], v[40:41]
	v_pk_add_f32 v[26:27], v[26:27], v[32:33]
	s_nop 0
	v_pk_add_f32 v[26:27], v[26:27], v[34:35]
	s_nop 0
	v_add_f32_e32 v26, v26, v27
	v_fmamk_f32 v26, v26, 0x3a800000, v152
	v_mul_f32_e32 v27, 0x4b800000, v26
	v_cmp_gt_f32_e32 vcc, s73, v26
	s_nop 1
	v_cndmask_b32_e32 v26, v26, v27, vcc
	v_rsq_f32_e32 v32, v26
	v_mad_i64_i32 v[26:27], s[36:37], v48, s78, v[120:121]
	v_lshl_add_u64 v[26:27], v[26:27], 0, v[122:123]
	v_mul_f32_e32 v33, 0x45800000, v32
	v_cndmask_b32_e32 v32, v32, v33, vcc
	v_pk_mul_f32 v[34:35], v[50:51], v[32:33] op_sel_hi:[1,0]
	v_pk_mul_f32 v[20:21], v[20:21], v[32:33] op_sel_hi:[1,0]
	v_pk_mul_f32 v[28:29], v[28:29], v[32:33] op_sel_hi:[1,0]
	v_pk_mul_f32 v[22:23], v[22:23], v[32:33] op_sel_hi:[1,0]
	v_pk_mul_f32 v[30:31], v[30:31], v[32:33] op_sel_hi:[1,0]
	v_pk_mul_f32 v[16:17], v[16:17], v[32:33] op_sel_hi:[1,0]
	v_pk_mul_f32 v[24:25], v[24:25], v[32:33] op_sel_hi:[1,0]
	v_pk_mul_f32 v[18:19], v[18:19], v[32:33] op_sel_hi:[1,0]
	v_mul_f32_e32 v32, 0xbfb8aa3b, v35
	v_mul_f32_e32 v33, 0xbfb8aa3b, v21
	v_mul_f32_e32 v36, 0xbfb8aa3b, v29
	v_mul_f32_e32 v39, 0xbfb8aa3b, v17
	v_exp_f32_e32 v32, v32
	v_mul_f32_e32 v37, 0xbfb8aa3b, v23
	v_mul_f32_e32 v41, 0xbfb8aa3b, v19
	v_exp_f32_e32 v33, v33
	v_exp_f32_e32 v36, v36
	v_exp_f32_e32 v39, v39
	v_mul_f32_e32 v38, 0xbfb8aa3b, v31
	v_mul_f32_e32 v40, 0xbfb8aa3b, v25
	v_exp_f32_e32 v37, v37
	v_exp_f32_e32 v41, v41
	v_exp_f32_e32 v38, v38
	v_exp_f32_e32 v40, v40
	v_add_f32_e32 v32, 1.0, v32
	v_add_f32_e32 v33, 1.0, v33
	v_add_f32_e32 v36, 1.0, v36
	v_add_f32_e32 v39, 1.0, v39
	v_rcp_f32_e32 v32, v32
	v_add_f32_e32 v37, 1.0, v37
	v_add_f32_e32 v41, 1.0, v41
	v_rcp_f32_e32 v33, v33
	v_rcp_f32_e32 v36, v36
	v_rcp_f32_e32 v39, v39
	v_add_f32_e32 v38, 1.0, v38
	v_add_f32_e32 v40, 1.0, v40
	v_rcp_f32_e32 v37, v37
	v_rcp_f32_e32 v41, v41
	v_rcp_f32_e32 v38, v38
	v_rcp_f32_e32 v40, v40
	v_mul_f32_e32 v32, v35, v32
	v_mul_f32_e32 v21, v21, v33
	v_mul_f32_e32 v29, v29, v36
	v_mul_f32_e32 v17, v17, v39
	v_mul_f32_e32 v32, v34, v32
	v_mul_f32_e32 v23, v23, v37
	v_mul_f32_e32 v19, v19, v41
	v_mul_f32_e32 v20, v20, v21
	v_mul_f32_e32 v21, v28, v29
	v_mul_f32_e32 v28, v16, v17
	v_cvt_pk_bf16_f32 v16, v32, v20
	v_add_u32_e32 v32, 0xb0, v144
	v_mul_f32_e32 v31, v31, v38
	v_mul_f32_e32 v25, v25, v40
	v_mul_f32_e32 v22, v22, v23
	v_mul_f32_e32 v19, v18, v19
	v_cvt_pk_bf16_f32 v17, v21, v22
	v_ashrrev_i32_e32 v33, 31, v32
	v_mul_f32_e32 v23, v30, v31
	v_mul_f32_e32 v24, v24, v25
	v_cvt_pk_bf16_f32 v18, v23, v28
	v_cvt_pk_bf16_f32 v19, v24, v19
	global_store_dwordx4 v[26:27], v[16:19], off
	v_mov_b32_e32 v34, v12
	v_mov_b32_e32 v35, v4
	v_lshlrev_b64 v[16:17], 6, v[32:33]
	v_lshl_add_u64 v[28:29], s[18:19], 0, v[16:17]
	global_load_dwordx4 v[16:19], v[28:29], off
	global_load_dwordx4 v[20:23], v[28:29], off offset:16
	global_load_dwordx4 v[24:27], v[28:29], off offset:32
	s_nop 0
	global_load_dwordx4 v[28:31], v[28:29], off offset:48
	v_mov_b32_e32 v4, v13
	v_mov_b32_e32 v12, v14
	v_mov_b32_e32 v13, v6
	v_mov_b32_e32 v6, v15
	v_mov_b32_e32 v14, v8
	v_mov_b32_e32 v15, v0
	v_mov_b32_e32 v0, v9
	v_mov_b32_e32 v8, v10
	v_mov_b32_e32 v9, v2
	v_mov_b32_e32 v2, v11
	s_waitcnt vmcnt(3)
	v_mov_b32_e32 v10, v17
	v_mov_b32_e32 v11, v18
	v_mov_b32_e32 v17, v19
	s_waitcnt vmcnt(2)
	v_mov_b32_e32 v18, v21
	v_mov_b32_e32 v19, v22
	v_mov_b32_e32 v21, v23
	v_pk_add_f32 v[10:11], v[10:11], v[16:17]
	v_pk_add_f32 v[16:17], v[18:19], v[20:21]
	v_pk_add_f32 v[10:11], v[10:11], v[10:11] op_sel:[0,1] op_sel_hi:[1,0]
	v_pk_add_f32 v[16:17], v[16:17], v[16:17] op_sel:[0,1] op_sel_hi:[1,0]
	s_waitcnt vmcnt(1)
	v_add_f32_e32 v22, v24, v25
	v_add_f32_e32 v24, v26, v27
	s_waitcnt vmcnt(0)
	v_mov_b32_e32 v23, v30
	v_mov_b32_e32 v25, v31
	v_mov_b32_e32 v11, v28
	v_mov_b32_e32 v17, v29
	v_pk_add_f32 v[18:19], v[22:23], v[24:25]
	v_pk_add_f32 v[10:11], v[10:11], v[16:17]
	s_nop 0
	v_pk_add_f32 v[10:11], v[10:11], v[18:19]
	s_nop 0
	v_add_f32_e32 v10, v10, v11
	v_fmamk_f32 v10, v10, 0x3a800000, v152
	v_mul_f32_e32 v11, 0x4b800000, v10
	v_cmp_gt_f32_e32 vcc, s73, v10
	s_nop 1
	v_cndmask_b32_e32 v10, v10, v11, vcc
	v_rsq_f32_e32 v16, v10
	v_mad_i64_i32 v[10:11], s[36:37], v32, s78, v[120:121]
	v_lshl_add_u64 v[10:11], v[10:11], 0, v[122:123]
	v_mul_f32_e32 v17, 0x45800000, v16
	v_cndmask_b32_e32 v16, v16, v17, vcc
	v_pk_mul_f32 v[2:3], v[2:3], v[16:17] op_sel_hi:[1,0]
	v_pk_mul_f32 v[18:19], v[34:35], v[16:17] op_sel_hi:[1,0]
	v_pk_mul_f32 v[4:5], v[4:5], v[16:17] op_sel_hi:[1,0]
	v_pk_mul_f32 v[12:13], v[12:13], v[16:17] op_sel_hi:[1,0]
	v_pk_mul_f32 v[6:7], v[6:7], v[16:17] op_sel_hi:[1,0]
	v_pk_mul_f32 v[14:15], v[14:15], v[16:17] op_sel_hi:[1,0]
	v_pk_mul_f32 v[0:1], v[0:1], v[16:17] op_sel_hi:[1,0]
	v_pk_mul_f32 v[8:9], v[8:9], v[16:17] op_sel_hi:[1,0]
	v_mul_f32_e32 v25, 0xbfb8aa3b, v3
	v_mul_f32_e32 v16, 0xbfb8aa3b, v19
	v_mul_f32_e32 v17, 0xbfb8aa3b, v5
	v_mul_f32_e32 v20, 0xbfb8aa3b, v13
	v_mul_f32_e32 v21, 0xbfb8aa3b, v7
	v_mul_f32_e32 v22, 0xbfb8aa3b, v15
	v_mul_f32_e32 v23, 0xbfb8aa3b, v1
	v_mul_f32_e32 v24, 0xbfb8aa3b, v9
	v_exp_f32_e32 v25, v25
	v_exp_f32_e32 v16, v16
	v_exp_f32_e32 v17, v17
	v_exp_f32_e32 v20, v20
	v_exp_f32_e32 v21, v21
	v_exp_f32_e32 v22, v22
	v_exp_f32_e32 v23, v23
	v_exp_f32_e32 v24, v24
	v_add_f32_e32 v25, 1.0, v25
	v_add_f32_e32 v16, 1.0, v16
	v_add_f32_e32 v17, 1.0, v17
	v_add_f32_e32 v20, 1.0, v20
	v_add_f32_e32 v21, 1.0, v21
	v_add_f32_e32 v22, 1.0, v22
	v_add_f32_e32 v23, 1.0, v23
	v_add_f32_e32 v24, 1.0, v24
	v_rcp_f32_e32 v25, v25
	v_rcp_f32_e32 v16, v16
	v_rcp_f32_e32 v17, v17
	v_rcp_f32_e32 v20, v20
	v_rcp_f32_e32 v21, v21
	v_rcp_f32_e32 v22, v22
	v_rcp_f32_e32 v23, v23
	v_rcp_f32_e32 v24, v24
	v_mul_f32_e32 v3, v3, v25
	v_mul_f32_e32 v16, v19, v16
	v_mul_f32_e32 v5, v5, v17
	v_mul_f32_e32 v13, v13, v20
	v_mul_f32_e32 v7, v7, v21
	v_mul_f32_e32 v15, v15, v22
	v_mul_f32_e32 v1, v1, v23
	v_mul_f32_e32 v9, v9, v24
	v_mul_f32_e32 v3, v2, v3
	s_andn2_b64 vcc, exec, s[14:15]
	s_mov_b64 s[14:15], -1
	v_mul_f32_e32 v16, v18, v16
	v_mul_f32_e32 v4, v4, v5
	v_mul_f32_e32 v5, v12, v13
	v_mul_f32_e32 v6, v6, v7
	v_mul_f32_e32 v7, v14, v15
	v_mul_f32_e32 v12, v0, v1
	v_mul_f32_e32 v8, v8, v9
	v_cvt_pk_bf16_f32 v0, v16, v4
	v_cvt_pk_bf16_f32 v1, v5, v6
	v_cvt_pk_bf16_f32 v2, v7, v12
	v_cvt_pk_bf16_f32 v3, v8, v3
	global_store_dwordx4 v[10:11], v[0:3], off
	s_cbranch_vccnz .LBB0_1705
	s_andn2_b64 vcc, exec, s[0:1]
	s_cbranch_vccnz .LBB0_1704
	s_barrier
	s_branch .LBB0_1704

.LBB0_2066:
	s_or_b64 exec, exec, s[0:1]
.LBB0_2067:
	s_cmp_eq_u32 s100, 1
	s_cbranch_scc0 .Lgb_full_5
	s_waitcnt vmcnt(0)
	s_barrier
	s_and_saveexec_b64 s[0:1], s[46:47]
	s_cbranch_execz .Lgb_done_5
	s_and_b32 s98, s2, 7
	s_lshl_b32 s98, s98, 6
	s_add_i32 s98, s98, 0x4a00
	v_mov_b32_e32 v250, s98
	v_mov_b32_e32 v251, 1
	global_atomic_add v252, v250, v251, s[66:67] sc0
	buffer_inv sc1
	s_lshr_b32 s98, s64, 3
	s_mul_i32 s98, s98, 6
	s_add_i32 s98, s98, -1
	v_add_u32_e32 v250, 0x200, v250
	s_waitcnt vmcnt(0)
	v_readfirstlane_b32 s99, v252
	s_cmp_eq_u32 s99, s98
	s_cbranch_scc0 .Lgb_wait_5
	global_atomic_add v250, v251, s[66:67]
	s_waitcnt vmcnt(0)
	s_branch .Lgb_done_5

.LBB0_2165:
	s_mov_b32 s101, -1
	s_getreg_b32 s14, hwreg(HW_REG_XCC_ID, 0, 4)
	s_waitcnt vmcnt(0)
	s_waitcnt lgkmcnt(0)
	s_barrier
	s_and_saveexec_b64 s[0:1], s[46:47]
	s_cbranch_execz .LBB0_2217
	s_add_i32 s15, 0, 0x20160
	v_mov_b32_e32 v0, s15
	s_waitcnt vmcnt(0) expcnt(0) lgkmcnt(0)
	ds_read_b32 v2, v0
	s_add_i32 s15, 0, 0x20164
	v_mov_b32_e32 v0, s15
	ds_read_b32 v0, v0
	s_and_b32 s51, s14, 15
	s_waitcnt lgkmcnt(1)
	v_cmp_ne_u32_e32 vcc, 0, v2
	s_cbranch_vccnz .LBB0_2181
	s_add_u32 s14, s66, 0x1200
	s_addc_u32 s15, s67, 0
	s_add_u32 s16, s66, 0x1400
	s_addc_u32 s17, s67, 0
	s_add_u32 s18, s66, 0x1500
	s_addc_u32 s19, s67, 0
	s_add_u32 s20, s66, 0x1600
	s_addc_u32 s21, s67, 0
	s_add_u32 s22, s66, 0x1700
	s_addc_u32 s23, s67, 0
	s_add_u32 s24, s66, 0x1800
	s_addc_u32 s25, s67, 0
	s_add_u32 s26, s66, 0x1900
	s_addc_u32 s27, s67, 0
	s_add_u32 s28, s66, 0x1a00
	s_addc_u32 s29, s67, 0
	s_add_u32 s30, s66, 0x1b00
	s_addc_u32 s31, s67, 0
	s_add_u32 s34, s66, 0x1c00
	s_addc_u32 s35, s67, 0
	s_add_u32 s36, s66, 0x1d00
	s_addc_u32 s37, s67, 0
	s_add_u32 s38, s66, 0x1e00
	s_addc_u32 s39, s67, 0
	s_add_u32 s40, s66, 0x1f00
	s_addc_u32 s41, s67, 0
	s_add_u32 s42, s66, 0x2000
	s_addc_u32 s43, s67, 0
	s_add_u32 s44, s66, 0x2100
	s_addc_u32 s45, s67, 0
	s_add_u32 s52, s66, 0x2200
	s_addc_u32 s53, s67, 0
	s_mul_i32 s70, s65, s74
	s_add_u32 s56, s66, 0x2300
	s_mul_i32 s70, s70, s64
	s_addc_u32 s57, s67, 0
	s_mov_b32 s71, 1
	v_mov_b32_e32 v16, 0
	s_branch .LBB0_2169

.LBB0_2183:
	s_or_b64 exec, exec, s[18:19]
	v_cvt_f32_u32_e32 v4, v2
	s_waitcnt vmcnt(0)
	v_readfirstlane_b32 s16, v3
	v_sub_u32_e32 v3, 0, v2
	v_rcp_iflag_f32_e32 v4, v4
	v_add_u32_e32 v5, s16, v1
	v_mul_f32_e32 v4, 0x4f7ffffe, v4
	v_cvt_u32_f32_e32 v4, v4
	v_mul_lo_u32 v1, v3, v4
	v_mul_hi_u32 v1, v4, v1
	v_add_u32_e32 v1, v4, v1
	v_mul_hi_u32 v1, v5, v1
	v_mul_lo_u32 v3, v1, v2
	v_sub_u32_e32 v3, v5, v3
	v_add_u32_e32 v4, 1, v1
	v_cmp_ge_u32_e32 vcc, v3, v2
	s_nop 1
	v_cndmask_b32_e32 v1, v1, v4, vcc
	v_sub_u32_e32 v4, v3, v2
	v_cndmask_b32_e32 v3, v3, v4, vcc
	v_add_u32_e32 v4, 1, v1
	v_cmp_ge_u32_e32 vcc, v3, v2
	v_add_u32_e32 v3, 1, v5
	s_nop 0
	v_cndmask_b32_e32 v1, v1, v4, vcc
	v_mul_lo_u32 v4, v2, v1
	v_add_u32_e32 v2, v4, v2
	v_cmp_ne_u32_e32 vcc, v3, v2
	s_and_saveexec_b64 s[16:17], vcc
	s_xor_b64 s[16:17], exec, s[16:17]
	s_cbranch_execz .LBB0_2197
	s_cmp_lt_u32 s2, 0
	s_cbranch_scc1 .Lsb_wait_h2
	s_cmp_lg_u32 s64, 0x100
	s_cbranch_scc1 .Lsb_wait_h2
	s_cmp_lg_u32 s100, 1
	s_cbranch_scc1 .Lsb_wait_h2
	v_readfirstlane_b32 s101, v1
	s_branch .LBB0_2197

.LBB0_2217:
	s_or_b64 exec, exec, s[0:1]
	s_cmp_eq_u32 s100, 1
	s_cbranch_scc0 .Lhb_skip_6
	s_and_saveexec_b64 s[0:1], s[46:47]
	s_cbranch_execz .Lhb_done_6
	s_and_b32 s98, s2, 7
	s_lshl_b32 s98, s98, 6
	s_add_i32 s98, s98, 0x4a00
	v_mov_b32_e32 v250, s98
	v_mov_b32_e32 v251, 1
	global_atomic_add v252, v250, v251, s[66:67] sc0
	buffer_inv sc1
	s_lshr_b32 s98, s64, 3
	s_mul_i32 s98, s98, 7
	s_add_i32 s98, s98, -1
	v_add_u32_e32 v250, 0x200, v250
	s_waitcnt vmcnt(0)
	v_readfirstlane_b32 s99, v252
	s_cmp_eq_u32 s99, s98
	s_cbranch_scc0 .Lhb_wait_6
	global_atomic_add v250, v251, s[66:67]
	s_waitcnt vmcnt(0)
	s_branch .Lhb_done_6

.Lhb_spin_6:
	global_load_dword v252, v250, s[66:67] sc1
	s_waitcnt vmcnt(0)
	v_readfirstlane_b32 s98, v252
	s_cmp_gt_u32 s98, 6
	s_cbranch_scc1 .Lhb_done_6
	s_sleep 1
	s_add_i32 s99, s99, 1
	s_cmp_lt_u32 s99, 0x8000
	s_cbranch_scc1 .Lhb_spin_6

.Lhb_skip_6:
	s_mov_b64 s[24:25], s[66:67]
	s_mov_b64 s[0:1], s[68:69]
	s_waitcnt lgkmcnt(0)
	v_mov_b32_e32 v0, v194
	s_mov_b32 s51, s64
	v_mov_b32_e32 v8, v194
	s_barrier
	s_and_b64 vcc, exec, s[8:9]
	v_readfirstlane_b32 s16, v8
	s_cbranch_vccnz .LBB0_2223
	s_lshr_b32 s0, s3, 29
	s_add_i32 s14, s2, s0
	s_and_b32 s0, s14, -8
	s_sub_i32 s15, s2, s0
	s_cmp_gt_i32 s15, -1
	s_cbranch_scc0 .LBB0_2220
	s_lshl_b32 s17, s15, 6
	s_cbranch_execz .LBB0_2221
	s_branch .LBB0_2222

.Lsb_cj_h2:
	s_barrier
	s_lshl_b32 s35, s14, 8
	s_add_i32 s35, s35, s63
	v_or_b32_e32 v152, s35, v139
	v_ashrrev_i32_e32 v153, 31, v152
	v_lshlrev_b64 v[154:155], 6, v[152:153]
	v_lshl_add_u64 v[154:155], s[24:25], 0, v[154:155]
	global_load_dwordx4 v[162:165], v[154:155], off
	global_load_dwordx4 v[166:169], v[154:155], off offset:16
	global_load_dwordx4 v[170:173], v[154:155], off offset:32
	global_load_dwordx4 v[174:177], v[154:155], off offset:48
	s_cmp_gt_i32 s0, 1
	s_cselect_b64 s[40:41], -1, 0
	s_lshl_b32 s31, s0, 8
	s_and_b64 s[0:1], exec, s[40:41]
	s_mov_b64 s[14:15], -1
	v_lshlrev_b32_e32 v136, 1, v138
	s_add_i32 s16, s31, 0xfffffe00
	s_waitcnt vmcnt(0)
	v_mov_b32_e32 v154, v163
	v_mov_b32_e32 v155, v164
	v_mov_b32_e32 v163, v165
	v_mov_b32_e32 v164, v167
	v_mov_b32_e32 v165, v168
	v_mov_b32_e32 v167, v169
	v_pk_add_f32 v[154:155], v[154:155], v[162:163]
	v_pk_add_f32 v[162:163], v[164:165], v[166:167]
	v_pk_add_f32 v[154:155], v[154:155], v[154:155] op_sel:[0,1] op_sel_hi:[1,0]
	v_pk_add_f32 v[162:163], v[162:163], v[162:163] op_sel:[0,1] op_sel_hi:[1,0]
	v_add_f32_e32 v168, v170, v171
	v_add_f32_e32 v170, v172, v173
	v_mov_b32_e32 v169, v176
	v_mov_b32_e32 v171, v177
	v_mov_b32_e32 v155, v174
	v_mov_b32_e32 v163, v175
	v_pk_add_f32 v[164:165], v[168:169], v[170:171]
	v_pk_add_f32 v[154:155], v[154:155], v[162:163]
	s_nop 0
	v_pk_add_f32 v[154:155], v[154:155], v[164:165]
	s_nop 0
	v_add_f32_e32 v153, v154, v155
	v_fmamk_f32 v153, v153, 0x3a800000, v160
	v_mul_f32_e32 v154, 0x4b800000, v153
	v_cmp_gt_f32_e32 vcc, s80, v153
	s_nop 1
	v_cndmask_b32_e32 v153, v153, v154, vcc
	v_rsq_f32_e32 v153, v153
	s_nop 0
	v_mul_f32_e32 v154, 0x45800000, v153
	v_cndmask_b32_e32 v154, v153, v154, vcc
	v_pk_mul_f32 v[162:163], v[122:123], v[154:155] op_sel_hi:[1,0]
	v_pk_mul_f32 v[122:123], v[120:121], v[154:155] op_sel_hi:[1,0]
	s_mov_b64 vcc, s[0:1]
	v_pk_mul_f32 v[126:127], v[126:127], v[154:155] op_sel_hi:[1,0]
	v_pk_mul_f32 v[124:125], v[124:125], v[154:155] op_sel_hi:[1,0]
	s_nop 0
	v_cvt_pk_bf16_f32 v120, v124, v125
	v_cvt_pk_bf16_f32 v121, v126, v127
	v_cvt_pk_bf16_f32 v122, v122, v123
	v_cvt_pk_bf16_f32 v123, v162, v163
	s_cbranch_vccz .LBB0_2241
	v_mov_b64_e32 v[124:125], s[20:21]
	v_mad_i64_i32 v[124:125], s[0:1], v152, s82, v[124:125]
	v_lshl_add_u64 v[124:125], s[16:17], 1, v[124:125]
	s_lshl_b32 s0, s70, 1
	s_mov_b32 s1, s17
	v_lshl_add_u64 v[124:125], v[124:125], 0, s[0:1]
	v_lshl_add_u64 v[124:125], v[124:125], 0, v[136:137]
	global_store_dwordx4 v[124:125], v[120:123], off
	s_mov_b64 s[14:15], 0

.LBB0_3164:
	s_cmp_eq_u32 s100, 1
	s_cbranch_scc0 .Lgb_full_7
	s_waitcnt vmcnt(0)
	s_barrier
	s_and_saveexec_b64 s[0:1], s[46:47]
	s_cbranch_execz .Lgb_done_7
	s_and_b32 s98, s2, 7
	s_lshl_b32 s98, s98, 6
	s_add_i32 s98, s98, 0x4a00
	v_mov_b32_e32 v250, s98
	v_mov_b32_e32 v251, 1
	global_atomic_add v252, v250, v251, s[66:67] sc0
	buffer_inv sc1
	s_lshr_b32 s98, s64, 3
	s_mul_i32 s98, s98, 8
	s_add_i32 s98, s98, -1
	v_add_u32_e32 v250, 0x200, v250
	s_waitcnt vmcnt(0)
	v_readfirstlane_b32 s99, v252
	s_cmp_eq_u32 s99, s98
	s_cbranch_scc0 .Lgb_wait_7
	global_atomic_add v250, v251, s[66:67]
	s_waitcnt vmcnt(0)
	s_branch .Lgb_done_7

.Lgb_spin_7:
	global_load_dword v252, v250, s[66:67] sc1
	s_waitcnt vmcnt(0)
	v_readfirstlane_b32 s98, v252
	s_cmp_gt_u32 s98, 7
	s_cbranch_scc1 .Lgb_done_7
	s_sleep 1
	s_add_i32 s99, s99, 1
	s_cmp_lt_u32 s99, 0x8000
	s_cbranch_scc1 .Lgb_spin_7

.LBB0_3258:
	s_mov_b32 s101, -1
	s_getreg_b32 s8, hwreg(HW_REG_XCC_ID, 0, 4)
	s_waitcnt vmcnt(0)
	s_waitcnt lgkmcnt(0)
	s_barrier
	s_and_saveexec_b64 s[0:1], s[46:47]
	s_cbranch_execz .LBB0_3310
	s_add_i32 s9, 0, 0x20160
	v_mov_b32_e32 v0, s9
	s_waitcnt vmcnt(0) expcnt(0) lgkmcnt(0)
	ds_read_b32 v2, v0
	s_add_i32 s9, 0, 0x20164
	v_mov_b32_e32 v0, s9
	ds_read_b32 v0, v0
	s_and_b32 s52, s8, 15
	s_waitcnt lgkmcnt(1)
	v_cmp_ne_u32_e32 vcc, 0, v2
	s_cbranch_vccnz .LBB0_3274
	s_add_u32 s8, s66, 0x1200
	s_addc_u32 s9, s67, 0
	s_add_u32 s10, s66, 0x1400
	s_addc_u32 s11, s67, 0
	s_add_u32 s12, s66, 0x1500
	s_addc_u32 s13, s67, 0
	s_add_u32 s14, s66, 0x1600
	s_addc_u32 s15, s67, 0
	s_add_u32 s16, s66, 0x1700
	s_addc_u32 s17, s67, 0
	s_add_u32 s18, s66, 0x1800
	s_addc_u32 s19, s67, 0
	s_add_u32 s20, s66, 0x1900
	s_addc_u32 s21, s67, 0
	s_add_u32 s22, s66, 0x1a00
	s_addc_u32 s23, s67, 0
	s_add_u32 s24, s66, 0x1b00
	s_addc_u32 s25, s67, 0
	s_add_u32 s26, s66, 0x1c00
	s_addc_u32 s27, s67, 0
	s_add_u32 s28, s66, 0x1d00
	s_addc_u32 s29, s67, 0
	s_add_u32 s30, s66, 0x1e00
	s_addc_u32 s31, s67, 0
	s_add_u32 s34, s66, 0x1f00
	s_addc_u32 s35, s67, 0
	s_add_u32 s36, s66, 0x2000
	s_addc_u32 s37, s67, 0
	s_add_u32 s38, s66, 0x2100
	s_addc_u32 s39, s67, 0
	s_add_u32 s40, s66, 0x2200
	s_addc_u32 s41, s67, 0
	s_mul_i32 s53, s65, s74
	s_add_u32 s42, s66, 0x2300
	s_mul_i32 s53, s53, s64
	s_addc_u32 s43, s67, 0
	s_mov_b32 s54, 1
	v_mov_b32_e32 v16, 0
	s_branch .LBB0_3262

.LBB0_3276:
	s_or_b64 exec, exec, s[12:13]
	v_cvt_f32_u32_e32 v4, v2
	s_waitcnt vmcnt(0)
	v_readfirstlane_b32 s10, v3
	v_sub_u32_e32 v3, 0, v2
	v_rcp_iflag_f32_e32 v4, v4
	v_add_u32_e32 v5, s10, v1
	v_mul_f32_e32 v4, 0x4f7ffffe, v4
	v_cvt_u32_f32_e32 v4, v4
	v_mul_lo_u32 v1, v3, v4
	v_mul_hi_u32 v1, v4, v1
	v_add_u32_e32 v1, v4, v1
	v_mul_hi_u32 v1, v5, v1
	v_mul_lo_u32 v3, v1, v2
	v_sub_u32_e32 v3, v5, v3
	v_add_u32_e32 v4, 1, v1
	v_cmp_ge_u32_e32 vcc, v3, v2
	s_nop 1
	v_cndmask_b32_e32 v1, v1, v4, vcc
	v_sub_u32_e32 v4, v3, v2
	v_cndmask_b32_e32 v3, v3, v4, vcc
	v_add_u32_e32 v4, 1, v1
	v_cmp_ge_u32_e32 vcc, v3, v2
	v_add_u32_e32 v3, 1, v5
	s_nop 0
	v_cndmask_b32_e32 v1, v1, v4, vcc
	v_mul_lo_u32 v4, v2, v1
	v_add_u32_e32 v2, v4, v2
	v_cmp_ne_u32_e32 vcc, v3, v2
	s_and_saveexec_b64 s[10:11], vcc
	s_xor_b64 s[10:11], exec, s[10:11]
	s_cbranch_execz .LBB0_3290
	s_cmp_lt_u32 s2, 0
	s_cbranch_scc1 .Lsb_wait_h3
	s_cmp_lg_u32 s64, 0x100
	s_cbranch_scc1 .Lsb_wait_h3
	s_cmp_lg_u32 s100, 1
	s_cbranch_scc1 .Lsb_wait_h3
	v_readfirstlane_b32 s101, v1
	s_branch .LBB0_3290

.LBB0_3310:
	s_or_b64 exec, exec, s[0:1]
	s_cmp_eq_u32 s100, 1
	s_cbranch_scc0 .Lhb_skip_8
	s_and_saveexec_b64 s[0:1], s[46:47]
	s_cbranch_execz .Lhb_done_8
	s_and_b32 s98, s2, 7
	s_lshl_b32 s98, s98, 6
	s_add_i32 s98, s98, 0x4a00
	v_mov_b32_e32 v250, s98
	v_mov_b32_e32 v251, 1
	global_atomic_add v252, v250, v251, s[66:67] sc0
	buffer_inv sc1
	s_lshr_b32 s98, s64, 3
	s_mul_i32 s98, s98, 9
	s_add_i32 s98, s98, -1
	v_add_u32_e32 v250, 0x200, v250
	s_waitcnt vmcnt(0)
	v_readfirstlane_b32 s99, v252
	s_cmp_eq_u32 s99, s98
	s_cbranch_scc0 .Lhb_wait_8
	global_atomic_add v250, v251, s[66:67]
	s_waitcnt vmcnt(0)
	s_branch .Lhb_done_8

.Lhb_spin_8:
	global_load_dword v252, v250, s[66:67] sc1
	s_waitcnt vmcnt(0)
	v_readfirstlane_b32 s98, v252
	s_cmp_gt_u32 s98, 8
	s_cbranch_scc1 .Lhb_done_8
	s_sleep 1
	s_add_i32 s99, s99, 1
	s_cmp_lt_u32 s99, 0x8000
	s_cbranch_scc1 .Lhb_spin_8

.Lhb_skip_8:
	s_mov_b64 s[10:11], s[66:67]
	s_mov_b64 s[0:1], s[68:69]
	s_waitcnt lgkmcnt(0)
	v_mov_b32_e32 v0, v194
	s_mov_b32 s34, s64
	v_mov_b32_e32 v9, v194
	s_barrier
	s_and_b64 vcc, exec, s[6:7]
	v_readfirstlane_b32 s7, v9
	s_cbranch_vccnz .LBB0_3326
	v_lshlrev_b32_e32 v0, 4, v9
	v_add_u32_e32 v1, 0x2000, v0
	v_ashrrev_i32_e32 v2, 31, v1
	v_lshrrev_b32_e32 v2, 22, v2
	v_add_u32_e32 v2, v1, v2
	v_ashrrev_i32_e32 v8, 10, v2
	v_mul_i32_i24_e32 v2, 0x400, v8
	v_sub_u32_e32 v1, v1, v2
	v_lshrrev_b32_e32 v2, 4, v1
	v_bitop3_b32 v1, v2, v1, 32 bitop3:0x6c
	v_ashrrev_i32_e32 v2, 31, v1
	v_lshrrev_b32_e32 v2, 26, v2
	v_add_u32_e32 v2, v1, v2
	v_lshlrev_b32_e32 v3, 3, v8
	v_ashrrev_i32_e32 v10, 6, v2
	v_and_b32_e32 v3, -16, v3
	v_add_u32_e32 v3, v10, v3
	v_and_b32_e32 v4, 3, v10
	s_mov_b32 s0, 0x1fffe0
	v_lshrrev_b32_e32 v5, 2, v3
	v_lshlrev_b32_e32 v6, 1, v3
	v_and_b32_e32 v2, 0xc0, v2
	v_and_or_b32 v4, v3, s0, v4
	v_and_b32_e32 v5, 4, v5
	v_and_b32_e32 v6, 24, v6
	v_sub_u32_e32 v1, v1, v2
	v_mov_b32_e32 v2, 1
	v_or3_b32 v4, v4, v5, v6
	v_lshlrev_b32_e32 v5, 5, v8
	v_ashrrev_i16_sdwa v1, v2, sext(v1) dst_sel:DWORD dst_unused:UNUSED_PAD src0_sel:DWORD src1_sel:BYTE_0
	v_and_b32_e32 v5, 32, v5
	v_bfe_i32 v11, v1, 0, 16
	v_add_lshl_u32 v1, v5, v11, 1
	v_lshl_add_u32 v128, v4, 11, v1
	v_lshl_add_u32 v130, v3, 11, v1
	v_bfe_i32 v1, v9, 27, 1
	v_lshrrev_b32_e32 v1, 22, v1
	v_add_u32_e32 v1, v0, v1
	v_and_b32_e32 v1, 0xfffffc00, v1
	v_sub_u32_e32 v0, v0, v1
	v_lshrrev_b32_e32 v1, 4, v0
	v_ashrrev_i32_e32 v3, 31, v9
	v_bitop3_b32 v0, v1, v0, 32 bitop3:0x6c
	v_lshrrev_b32_e32 v3, 26, v3
	v_ashrrev_i32_e32 v1, 31, v0
	v_add_u32_e32 v3, v9, v3
	v_lshrrev_b32_e32 v1, 26, v1
	v_ashrrev_i32_e32 v13, 6, v3
	s_add_u32 s35, s10, 0x3800000
	v_add_u32_e32 v1, v0, v1
	v_lshlrev_b32_e32 v3, 3, v13
	s_addc_u32 s36, s11, 0
	v_ashrrev_i32_e32 v12, 6, v1
	v_and_b32_e32 v3, -16, v3
	s_add_u32 s37, s10, 0x1180000
	v_add_u32_e32 v3, v12, v3
	v_and_b32_e32 v4, 3, v12
	s_addc_u32 s38, s11, 0
	v_and_or_b32 v4, v3, s0, v4
	s_lshr_b32 s0, s3, 29
	s_add_i32 s0, s2, s0
	s_ashr_i32 s12, s7, 6
	s_ashr_i32 s1, s0, 3
	s_and_b32 s0, s0, -8
	s_ashr_i32 s14, s7, 8
	s_lshl_b32 s39, s12, 10
	s_sub_i32 s0, s2, s0
	s_cmp_lt_i32 s0, 0
	s_movk_i32 s40, 0xb1
	s_cselect_b32 s6, s40, 0xb0
	s_mul_i32 s0, s0, s6
	s_add_i32 s0, s0, s1
	s_mul_hi_i32 s1, s0, 0x2e8ba2e9
	s_lshr_b32 s6, s1, 31
	s_ashr_i32 s1, s1, 5
	s_add_i32 s1, s1, s6
	s_lshl_b32 s8, s1, 3
	s_mulk_i32 s1, 0xb0
	s_sub_i32 s0, s0, s1
	s_sext_i32_i16 s1, s0
	s_bfe_u32 s1, s1, 0x3001c
	s_add_i32 s1, s0, s1
	s_sext_i32_i16 s6, s1
	s_and_b32 s1, s1, 0xfff8
	s_sub_i32 s0, s0, s1
	s_sext_i32_i16 s0, s0
	v_lshrrev_b32_e32 v5, 2, v3
	v_lshlrev_b32_e32 v6, 1, v3
	v_and_b32_e32 v1, 0xc0, v1
	s_lshr_b32 s6, s6, 3
	s_add_i32 s24, s8, s0
	v_and_b32_e32 v5, 4, v5
	v_and_b32_e32 v6, 24, v6
	v_sub_u32_e32 v0, v0, v1
	s_ashr_i32 s25, s24, 31
	s_bfe_i64 s[8:9], s[6:7], 0x100000
	v_or3_b32 v4, v4, v5, v6
	v_lshlrev_b32_e32 v5, 5, v13
	v_ashrrev_i16_sdwa v0, v2, sext(v0) dst_sel:DWORD dst_unused:UNUSED_PAD src0_sel:DWORD src1_sel:BYTE_0
	s_lshl_b64 s[0:1], s[24:25], 19
	s_lshl_b64 s[8:9], s[8:9], 19
	v_and_b32_e32 v5, 32, v5
	v_bfe_i32 v14, v0, 0, 16
	s_add_u32 s28, s37, s8
	v_add_lshl_u32 v0, v5, v14, 1
	s_addc_u32 s29, s38, s9
	s_add_i32 s25, s39, 0
	v_lshl_add_u32 v132, v4, 11, v0
	s_add_i32 m0, s25, 0x10000
	v_lshl_add_u32 v134, v3, 11, v0
	global_load_lds_dwordx4 v132, s[28:29]
	s_add_i32 m0, s25, 0x12000
	s_add_u32 s8, s28, 0x40000
	global_load_lds_dwordx4 v128, s[28:29]
	s_addc_u32 s9, s29, 0
	s_add_i32 m0, s25, 0x14000
	v_mov_b32_e32 v133, 0
	global_load_lds_dwordx4 v132, s[8:9]
	s_add_i32 m0, s25, 0x16000
	s_add_u32 s26, s35, s0
	s_addc_u32 s27, s36, s1
	s_add_i32 s41, s25, 0x2000
	global_load_lds_dwordx4 v128, s[8:9]
	s_mov_b32 m0, s25
	s_add_u32 s0, s26, 0x40000
	global_load_lds_dwordx4 v134, s[26:27]
	s_mov_b32 m0, s41
	s_addc_u32 s1, s27, 0
	s_add_i32 s42, s25, 0x4000
	global_load_lds_dwordx4 v130, s[26:27]
	s_mov_b32 m0, s42
	s_add_i32 s43, s25, 0x6000
	global_load_lds_dwordx4 v134, s[0:1]
	s_mov_b32 m0, s43
	v_mov_b32_e32 v129, v133
	global_load_lds_dwordx4 v130, s[0:1]
	v_mov_b32_e32 v135, v133
	v_mov_b32_e32 v131, v133
	s_cmp_eq_u32 s14, 1
	s_mov_b32 s44, 0
	v_lshl_add_u64 v[6:7], s[28:29], 0, v[132:133]
	v_lshl_add_u64 v[4:5], s[28:29], 0, v[128:129]
	v_lshl_add_u64 v[0:1], s[26:27], 0, v[134:135]
	s_cselect_b64 s[0:1], -1, 0
	s_cmp_lg_u32 s14, 1
	v_lshl_add_u64 v[2:3], s[26:27], 0, v[130:131]
	s_cbranch_scc1 .LBB0_3313
	s_barrier

.Lsb_cj_h3:
	s_barrier
	v_lshl_add_u32 v144, s24, 8, v146
	v_ashrrev_i32_e32 v145, 31, v144
	v_lshlrev_b64 v[154:155], 6, v[144:145]
	v_lshl_add_u64 v[166:167], s[10:11], 0, v[154:155]
	global_load_dwordx4 v[154:157], v[166:167], off
	global_load_dwordx4 v[158:161], v[166:167], off offset:16
	global_load_dwordx4 v[162:165], v[166:167], off offset:32
	s_nop 0
	global_load_dwordx4 v[166:169], v[166:167], off offset:48
	v_mov_b32_e32 v174, v122
	v_mov_b32_e32 v175, v114
	v_mov_b32_e32 v114, v123
	v_mov_b32_e32 v172, v124
	v_mov_b32_e32 v173, v116
	v_mov_b32_e32 v116, v125
	v_mov_b32_e32 v124, v126
	v_mov_b32_e32 v125, v118
	v_mov_b32_e32 v118, v127
	v_mov_b32_e32 v127, v112
	v_mov_b32_e32 v112, v121
	v_mov_b32_e32 v126, v120
	v_lshl_or_b32 v170, s54, 7, v148
	v_mov_b64_e32 v[120:121], s[8:9]
	v_ashrrev_i32_e32 v171, 31, v170
	s_waitcnt vmcnt(0)
	v_mov_b32_e32 v122, v155
	v_mov_b32_e32 v123, v156
	v_mov_b32_e32 v155, v157
	v_mov_b32_e32 v156, v159
	v_mov_b32_e32 v157, v160
	v_mov_b32_e32 v159, v161
	v_pk_add_f32 v[122:123], v[122:123], v[154:155]
	v_pk_add_f32 v[154:155], v[156:157], v[158:159]
	v_pk_add_f32 v[122:123], v[122:123], v[122:123] op_sel:[0,1] op_sel_hi:[1,0]
	v_pk_add_f32 v[154:155], v[154:155], v[154:155] op_sel:[0,1] op_sel_hi:[1,0]
	v_add_f32_e32 v160, v162, v163
	v_add_f32_e32 v162, v164, v165
	v_mov_b32_e32 v161, v168
	v_mov_b32_e32 v163, v169
	v_mov_b32_e32 v123, v166
	v_mov_b32_e32 v155, v167
	v_pk_add_f32 v[156:157], v[160:161], v[162:163]
	v_pk_add_f32 v[122:123], v[122:123], v[154:155]
	v_mad_i64_i32 v[154:155], s[26:27], v144, s53, v[120:121]
	v_pk_add_f32 v[122:123], v[122:123], v[156:157]
	s_nop 0
	v_add_f32_e32 v122, v122, v123
	v_fmamk_f32 v122, v122, 0x3a800000, v152
	v_mul_f32_e32 v123, 0x4b800000, v122
	v_cmp_gt_f32_e32 vcc, s52, v122
	s_nop 1
	v_cndmask_b32_e32 v122, v122, v123, vcc
	v_rsq_f32_e32 v145, v122
	v_lshlrev_b64 v[122:123], 1, v[170:171]
	v_lshl_add_u64 v[154:155], v[154:155], 0, v[122:123]
	v_mul_f32_e32 v153, 0x45800000, v145
	v_cndmask_b32_e32 v156, v145, v153, vcc
	v_pk_mul_f32 v[158:159], v[172:173], v[156:157] op_sel_hi:[1,0]
	v_pk_mul_f32 v[116:117], v[116:117], v[156:157] op_sel_hi:[1,0]
	v_pk_mul_f32 v[124:125], v[124:125], v[156:157] op_sel_hi:[1,0]
	v_pk_mul_f32 v[118:119], v[118:119], v[156:157] op_sel_hi:[1,0]
	v_pk_mul_f32 v[112:113], v[112:113], v[156:157] op_sel_hi:[1,0]
	v_pk_mul_f32 v[114:115], v[114:115], v[156:157] op_sel_hi:[1,0]
	v_mul_f32_e32 v145, 0xbfb8aa3b, v159
	v_pk_mul_f32 v[126:127], v[126:127], v[156:157] op_sel_hi:[1,0]
	v_pk_mul_f32 v[160:161], v[174:175], v[156:157] op_sel_hi:[1,0]
	v_mul_f32_e32 v153, 0xbfb8aa3b, v117
	v_mul_f32_e32 v156, 0xbfb8aa3b, v125
	v_mul_f32_e32 v157, 0xbfb8aa3b, v119
	v_mul_f32_e32 v163, 0xbfb8aa3b, v113
	v_mul_f32_e32 v165, 0xbfb8aa3b, v115
	v_exp_f32_e32 v145, v145
	v_mul_f32_e32 v162, 0xbfb8aa3b, v127
	v_mul_f32_e32 v164, 0xbfb8aa3b, v161
	v_exp_f32_e32 v153, v153
	v_exp_f32_e32 v156, v156
	v_exp_f32_e32 v157, v157
	v_exp_f32_e32 v163, v163
	v_exp_f32_e32 v165, v165
	v_exp_f32_e32 v162, v162
	v_exp_f32_e32 v164, v164
	v_add_f32_e32 v145, 1.0, v145
	v_add_f32_e32 v153, 1.0, v153
	v_add_f32_e32 v156, 1.0, v156
	v_add_f32_e32 v157, 1.0, v157
	v_add_f32_e32 v163, 1.0, v163
	v_add_f32_e32 v165, 1.0, v165
	v_rcp_f32_e32 v145, v145
	v_add_f32_e32 v162, 1.0, v162
	v_add_f32_e32 v164, 1.0, v164
	v_rcp_f32_e32 v153, v153
	v_rcp_f32_e32 v156, v156
	v_rcp_f32_e32 v157, v157
	v_rcp_f32_e32 v163, v163
	v_rcp_f32_e32 v165, v165
	v_rcp_f32_e32 v162, v162
	v_rcp_f32_e32 v164, v164
	v_mul_f32_e32 v145, v159, v145
	v_mul_f32_e32 v117, v117, v153
	v_mul_f32_e32 v125, v125, v156
	v_mul_f32_e32 v119, v119, v157
	v_mul_f32_e32 v113, v113, v163
	v_mul_f32_e32 v115, v115, v165
	v_mul_f32_e32 v145, v158, v145
	v_or_b32_e32 v158, 16, v144
	v_mul_f32_e32 v127, v127, v162
	v_mul_f32_e32 v153, v161, v164
	v_mul_f32_e32 v116, v116, v117
	v_mul_f32_e32 v117, v124, v125
	v_mul_f32_e32 v118, v118, v119
	v_mul_f32_e32 v124, v112, v113
	v_mul_f32_e32 v115, v114, v115
	v_cvt_pk_bf16_f32 v112, v145, v116
	v_cvt_pk_bf16_f32 v113, v117, v118
	v_ashrrev_i32_e32 v159, 31, v158
	v_mul_f32_e32 v119, v126, v127
	v_mul_f32_e32 v125, v160, v153
	v_cvt_pk_bf16_f32 v114, v119, v124
	v_cvt_pk_bf16_f32 v115, v125, v115
	global_store_dwordx4 v[154:155], v[112:115], off
	v_mov_b32_e32 v160, v108
	v_mov_b32_e32 v161, v100
	v_lshlrev_b64 v[112:113], 6, v[158:159]
	v_lshl_add_u64 v[154:155], s[10:11], 0, v[112:113]
	global_load_dwordx4 v[112:115], v[154:155], off
	global_load_dwordx4 v[116:119], v[154:155], off offset:16
	global_load_dwordx4 v[124:127], v[154:155], off offset:32
	s_nop 0
	global_load_dwordx4 v[154:157], v[154:155], off offset:48
	v_mov_b32_e32 v100, v109
	v_mov_b32_e32 v108, v110
	v_mov_b32_e32 v109, v102
	v_mov_b32_e32 v102, v111
	v_mov_b32_e32 v110, v104
	v_mov_b32_e32 v111, v96
	v_mov_b32_e32 v96, v105
	v_mov_b32_e32 v104, v106
	v_mov_b32_e32 v105, v98
	v_mov_b32_e32 v98, v107
	s_waitcnt vmcnt(3)
	v_mov_b32_e32 v106, v113
	v_mov_b32_e32 v107, v114
	v_mov_b32_e32 v113, v115
	s_waitcnt vmcnt(2)
	v_mov_b32_e32 v114, v117
	v_mov_b32_e32 v115, v118
	v_mov_b32_e32 v117, v119
	v_pk_add_f32 v[106:107], v[106:107], v[112:113]
	v_pk_add_f32 v[112:113], v[114:115], v[116:117]
	v_pk_add_f32 v[106:107], v[106:107], v[106:107] op_sel:[0,1] op_sel_hi:[1,0]
	v_pk_add_f32 v[112:113], v[112:113], v[112:113] op_sel:[0,1] op_sel_hi:[1,0]
	s_waitcnt vmcnt(1)
	v_add_f32_e32 v118, v124, v125
	v_add_f32_e32 v124, v126, v127
	s_waitcnt vmcnt(0)
	v_mov_b32_e32 v119, v156
	v_mov_b32_e32 v125, v157
	v_mov_b32_e32 v107, v154
	v_mov_b32_e32 v113, v155
	v_pk_add_f32 v[114:115], v[118:119], v[124:125]
	v_pk_add_f32 v[106:107], v[106:107], v[112:113]
	s_nop 0
	v_pk_add_f32 v[106:107], v[106:107], v[114:115]
	s_nop 0
	v_add_f32_e32 v106, v106, v107
	v_fmamk_f32 v106, v106, 0x3a800000, v152
	v_mul_f32_e32 v107, 0x4b800000, v106
	v_cmp_gt_f32_e32 vcc, s52, v106
	s_nop 1
	v_cndmask_b32_e32 v106, v106, v107, vcc
	v_rsq_f32_e32 v112, v106
	v_mad_i64_i32 v[106:107], s[26:27], v158, s53, v[120:121]
	v_lshl_add_u64 v[106:107], v[106:107], 0, v[122:123]
	v_mul_f32_e32 v113, 0x45800000, v112
	v_cndmask_b32_e32 v112, v112, v113, vcc
	v_pk_mul_f32 v[114:115], v[160:161], v[112:113] op_sel_hi:[1,0]
	v_pk_mul_f32 v[100:101], v[100:101], v[112:113] op_sel_hi:[1,0]
	v_pk_mul_f32 v[108:109], v[108:109], v[112:113] op_sel_hi:[1,0]
	v_pk_mul_f32 v[102:103], v[102:103], v[112:113] op_sel_hi:[1,0]
	v_pk_mul_f32 v[110:111], v[110:111], v[112:113] op_sel_hi:[1,0]
	v_pk_mul_f32 v[96:97], v[96:97], v[112:113] op_sel_hi:[1,0]
	v_pk_mul_f32 v[104:105], v[104:105], v[112:113] op_sel_hi:[1,0]
	v_pk_mul_f32 v[98:99], v[98:99], v[112:113] op_sel_hi:[1,0]
	v_mul_f32_e32 v112, 0xbfb8aa3b, v115
	v_mul_f32_e32 v113, 0xbfb8aa3b, v101
	v_mul_f32_e32 v116, 0xbfb8aa3b, v109
	v_mul_f32_e32 v119, 0xbfb8aa3b, v97
	v_exp_f32_e32 v112, v112
	v_mul_f32_e32 v117, 0xbfb8aa3b, v103
	v_mul_f32_e32 v125, 0xbfb8aa3b, v99
	v_exp_f32_e32 v113, v113
	v_exp_f32_e32 v116, v116
	v_exp_f32_e32 v119, v119
	v_mul_f32_e32 v118, 0xbfb8aa3b, v111
	v_mul_f32_e32 v124, 0xbfb8aa3b, v105
	v_exp_f32_e32 v117, v117
	v_exp_f32_e32 v125, v125
	v_exp_f32_e32 v118, v118
	v_exp_f32_e32 v124, v124
	v_add_f32_e32 v112, 1.0, v112
	v_add_f32_e32 v113, 1.0, v113
	v_add_f32_e32 v116, 1.0, v116
	v_add_f32_e32 v119, 1.0, v119
	v_rcp_f32_e32 v112, v112
	v_add_f32_e32 v117, 1.0, v117
	v_add_f32_e32 v125, 1.0, v125
	v_rcp_f32_e32 v113, v113
	v_rcp_f32_e32 v116, v116
	v_rcp_f32_e32 v119, v119
	v_add_f32_e32 v118, 1.0, v118
	v_add_f32_e32 v124, 1.0, v124
	v_rcp_f32_e32 v117, v117
	v_rcp_f32_e32 v125, v125
	v_rcp_f32_e32 v118, v118
	v_rcp_f32_e32 v124, v124
	v_mul_f32_e32 v112, v115, v112
	v_mul_f32_e32 v101, v101, v113
	v_mul_f32_e32 v109, v109, v116
	v_mul_f32_e32 v97, v97, v119
	v_mul_f32_e32 v112, v114, v112
	v_mul_f32_e32 v103, v103, v117
	v_mul_f32_e32 v99, v99, v125
	v_mul_f32_e32 v100, v100, v101
	v_mul_f32_e32 v101, v108, v109
	v_mul_f32_e32 v108, v96, v97
	v_cvt_pk_bf16_f32 v96, v112, v100
	v_or_b32_e32 v112, 32, v144
	v_mul_f32_e32 v111, v111, v118
	v_mul_f32_e32 v105, v105, v124
	v_mul_f32_e32 v102, v102, v103
	v_mul_f32_e32 v99, v98, v99
	v_cvt_pk_bf16_f32 v97, v101, v102
	v_ashrrev_i32_e32 v113, 31, v112
	v_mul_f32_e32 v103, v110, v111
	v_mul_f32_e32 v104, v104, v105
	v_cvt_pk_bf16_f32 v98, v103, v108
	v_cvt_pk_bf16_f32 v99, v104, v99
	global_store_dwordx4 v[106:107], v[96:99], off
	v_mov_b32_e32 v114, v92
	v_mov_b32_e32 v115, v84
	v_lshlrev_b64 v[96:97], 6, v[112:113]
	v_lshl_add_u64 v[108:109], s[10:11], 0, v[96:97]
	global_load_dwordx4 v[96:99], v[108:109], off
	global_load_dwordx4 v[100:103], v[108:109], off offset:16
	global_load_dwordx4 v[104:107], v[108:109], off offset:32
	s_nop 0
	global_load_dwordx4 v[108:111], v[108:109], off offset:48
	v_mov_b32_e32 v84, v93
	v_mov_b32_e32 v92, v94
	v_mov_b32_e32 v93, v86
	v_mov_b32_e32 v86, v95
	v_mov_b32_e32 v94, v88
	v_mov_b32_e32 v95, v80
	v_mov_b32_e32 v80, v89
	v_mov_b32_e32 v88, v90
	v_mov_b32_e32 v89, v82
	v_mov_b32_e32 v82, v91
	s_waitcnt vmcnt(3)
	v_mov_b32_e32 v90, v97
	v_mov_b32_e32 v91, v98
	v_mov_b32_e32 v97, v99
	s_waitcnt vmcnt(2)
	v_mov_b32_e32 v98, v101
	v_mov_b32_e32 v99, v102
	v_mov_b32_e32 v101, v103
	v_pk_add_f32 v[90:91], v[90:91], v[96:97]
	v_pk_add_f32 v[96:97], v[98:99], v[100:101]
	v_pk_add_f32 v[90:91], v[90:91], v[90:91] op_sel:[0,1] op_sel_hi:[1,0]
	v_pk_add_f32 v[96:97], v[96:97], v[96:97] op_sel:[0,1] op_sel_hi:[1,0]
	s_waitcnt vmcnt(1)
	v_add_f32_e32 v102, v104, v105
	v_add_f32_e32 v104, v106, v107
	s_waitcnt vmcnt(0)
	v_mov_b32_e32 v103, v110
	v_mov_b32_e32 v105, v111
	v_mov_b32_e32 v91, v108
	v_mov_b32_e32 v97, v109
	v_pk_add_f32 v[98:99], v[102:103], v[104:105]
	v_pk_add_f32 v[90:91], v[90:91], v[96:97]
	s_nop 0
	v_pk_add_f32 v[90:91], v[90:91], v[98:99]
	s_nop 0
	v_add_f32_e32 v90, v90, v91
	v_fmamk_f32 v90, v90, 0x3a800000, v152
	v_mul_f32_e32 v91, 0x4b800000, v90
	v_cmp_gt_f32_e32 vcc, s52, v90
	s_nop 1
	v_cndmask_b32_e32 v90, v90, v91, vcc
	v_rsq_f32_e32 v96, v90
	v_mad_i64_i32 v[90:91], s[26:27], v112, s53, v[120:121]
	v_lshl_add_u64 v[90:91], v[90:91], 0, v[122:123]
	v_mul_f32_e32 v97, 0x45800000, v96
	v_cndmask_b32_e32 v96, v96, v97, vcc
	v_pk_mul_f32 v[98:99], v[114:115], v[96:97] op_sel_hi:[1,0]
	v_pk_mul_f32 v[84:85], v[84:85], v[96:97] op_sel_hi:[1,0]
	v_pk_mul_f32 v[92:93], v[92:93], v[96:97] op_sel_hi:[1,0]
	v_pk_mul_f32 v[86:87], v[86:87], v[96:97] op_sel_hi:[1,0]
	v_pk_mul_f32 v[94:95], v[94:95], v[96:97] op_sel_hi:[1,0]
	v_pk_mul_f32 v[80:81], v[80:81], v[96:97] op_sel_hi:[1,0]
	v_pk_mul_f32 v[88:89], v[88:89], v[96:97] op_sel_hi:[1,0]
	v_pk_mul_f32 v[82:83], v[82:83], v[96:97] op_sel_hi:[1,0]
	v_mul_f32_e32 v96, 0xbfb8aa3b, v99
	v_mul_f32_e32 v97, 0xbfb8aa3b, v85
	v_mul_f32_e32 v100, 0xbfb8aa3b, v93
	v_mul_f32_e32 v103, 0xbfb8aa3b, v81
	v_exp_f32_e32 v96, v96
	v_mul_f32_e32 v101, 0xbfb8aa3b, v87
	v_mul_f32_e32 v105, 0xbfb8aa3b, v83
	v_exp_f32_e32 v97, v97
	v_exp_f32_e32 v100, v100
	v_exp_f32_e32 v103, v103
	v_mul_f32_e32 v102, 0xbfb8aa3b, v95
	v_mul_f32_e32 v104, 0xbfb8aa3b, v89
	v_exp_f32_e32 v101, v101
	v_exp_f32_e32 v105, v105
	v_exp_f32_e32 v102, v102
	v_exp_f32_e32 v104, v104
	v_add_f32_e32 v96, 1.0, v96
	v_add_f32_e32 v97, 1.0, v97
	v_add_f32_e32 v100, 1.0, v100
	v_add_f32_e32 v103, 1.0, v103
	v_rcp_f32_e32 v96, v96
	v_add_f32_e32 v101, 1.0, v101
	v_add_f32_e32 v105, 1.0, v105
	v_rcp_f32_e32 v97, v97
	v_rcp_f32_e32 v100, v100
	v_rcp_f32_e32 v103, v103
	v_add_f32_e32 v102, 1.0, v102
	v_add_f32_e32 v104, 1.0, v104
	v_rcp_f32_e32 v101, v101
	v_rcp_f32_e32 v105, v105
	v_rcp_f32_e32 v102, v102
	v_rcp_f32_e32 v104, v104
	v_mul_f32_e32 v96, v99, v96
	v_mul_f32_e32 v85, v85, v97
	v_mul_f32_e32 v93, v93, v100
	v_mul_f32_e32 v81, v81, v103
	v_mul_f32_e32 v96, v98, v96
	v_mul_f32_e32 v87, v87, v101
	v_mul_f32_e32 v83, v83, v105
	v_mul_f32_e32 v84, v84, v85
	v_mul_f32_e32 v85, v92, v93
	v_mul_f32_e32 v92, v80, v81
	v_cvt_pk_bf16_f32 v80, v96, v84
	v_or_b32_e32 v96, 48, v144
	v_mul_f32_e32 v95, v95, v102
	v_mul_f32_e32 v89, v89, v104
	v_mul_f32_e32 v86, v86, v87
	v_mul_f32_e32 v83, v82, v83
	v_cvt_pk_bf16_f32 v81, v85, v86
	v_ashrrev_i32_e32 v97, 31, v96
	v_mul_f32_e32 v87, v94, v95
	v_mul_f32_e32 v88, v88, v89
	v_cvt_pk_bf16_f32 v82, v87, v92
	v_cvt_pk_bf16_f32 v83, v88, v83
	global_store_dwordx4 v[90:91], v[80:83], off
	v_mov_b32_e32 v98, v76
	v_mov_b32_e32 v99, v68
	v_lshlrev_b64 v[80:81], 6, v[96:97]
	v_lshl_add_u64 v[92:93], s[10:11], 0, v[80:81]
	global_load_dwordx4 v[80:83], v[92:93], off
	global_load_dwordx4 v[84:87], v[92:93], off offset:16
	global_load_dwordx4 v[88:91], v[92:93], off offset:32
	s_nop 0
	global_load_dwordx4 v[92:95], v[92:93], off offset:48
	v_mov_b32_e32 v68, v77
	v_mov_b32_e32 v76, v78
	v_mov_b32_e32 v77, v70
	v_mov_b32_e32 v70, v79
	v_mov_b32_e32 v78, v72
	v_mov_b32_e32 v79, v64
	v_mov_b32_e32 v64, v73
	v_mov_b32_e32 v72, v74
	v_mov_b32_e32 v73, v66
	v_mov_b32_e32 v66, v75
	s_waitcnt vmcnt(3)
	v_mov_b32_e32 v74, v81
	v_mov_b32_e32 v75, v82
	v_mov_b32_e32 v81, v83
	s_waitcnt vmcnt(2)
	v_mov_b32_e32 v82, v85
	v_mov_b32_e32 v83, v86
	v_mov_b32_e32 v85, v87
	v_pk_add_f32 v[74:75], v[74:75], v[80:81]
	v_pk_add_f32 v[80:81], v[82:83], v[84:85]
	v_pk_add_f32 v[74:75], v[74:75], v[74:75] op_sel:[0,1] op_sel_hi:[1,0]
	v_pk_add_f32 v[80:81], v[80:81], v[80:81] op_sel:[0,1] op_sel_hi:[1,0]
	s_waitcnt vmcnt(1)
	v_add_f32_e32 v86, v88, v89
	v_add_f32_e32 v88, v90, v91
	s_waitcnt vmcnt(0)
	v_mov_b32_e32 v87, v94
	v_mov_b32_e32 v89, v95
	v_mov_b32_e32 v75, v92
	v_mov_b32_e32 v81, v93
	v_pk_add_f32 v[82:83], v[86:87], v[88:89]
	v_pk_add_f32 v[74:75], v[74:75], v[80:81]
	s_nop 0
	v_pk_add_f32 v[74:75], v[74:75], v[82:83]
	s_nop 0
	v_add_f32_e32 v74, v74, v75
	v_fmamk_f32 v74, v74, 0x3a800000, v152
	v_mul_f32_e32 v75, 0x4b800000, v74
	v_cmp_gt_f32_e32 vcc, s52, v74
	s_nop 1
	v_cndmask_b32_e32 v74, v74, v75, vcc
	v_rsq_f32_e32 v80, v74
	v_mad_i64_i32 v[74:75], s[26:27], v96, s53, v[120:121]
	v_lshl_add_u64 v[74:75], v[74:75], 0, v[122:123]
	v_mul_f32_e32 v81, 0x45800000, v80
	v_cndmask_b32_e32 v80, v80, v81, vcc
	v_pk_mul_f32 v[82:83], v[98:99], v[80:81] op_sel_hi:[1,0]
	v_pk_mul_f32 v[68:69], v[68:69], v[80:81] op_sel_hi:[1,0]
	v_pk_mul_f32 v[76:77], v[76:77], v[80:81] op_sel_hi:[1,0]
	v_pk_mul_f32 v[70:71], v[70:71], v[80:81] op_sel_hi:[1,0]
	v_pk_mul_f32 v[78:79], v[78:79], v[80:81] op_sel_hi:[1,0]
	v_pk_mul_f32 v[64:65], v[64:65], v[80:81] op_sel_hi:[1,0]
	v_pk_mul_f32 v[72:73], v[72:73], v[80:81] op_sel_hi:[1,0]
	v_pk_mul_f32 v[66:67], v[66:67], v[80:81] op_sel_hi:[1,0]
	v_mul_f32_e32 v80, 0xbfb8aa3b, v83
	v_mul_f32_e32 v81, 0xbfb8aa3b, v69
	v_mul_f32_e32 v84, 0xbfb8aa3b, v77
	v_mul_f32_e32 v87, 0xbfb8aa3b, v65
	v_exp_f32_e32 v80, v80
	v_mul_f32_e32 v85, 0xbfb8aa3b, v71
	v_mul_f32_e32 v89, 0xbfb8aa3b, v67
	v_exp_f32_e32 v81, v81
	v_exp_f32_e32 v84, v84
	v_exp_f32_e32 v87, v87
	v_mul_f32_e32 v86, 0xbfb8aa3b, v79
	v_mul_f32_e32 v88, 0xbfb8aa3b, v73
	v_exp_f32_e32 v85, v85
	v_exp_f32_e32 v89, v89
	v_exp_f32_e32 v86, v86
	v_exp_f32_e32 v88, v88
	v_add_f32_e32 v80, 1.0, v80
	v_add_f32_e32 v81, 1.0, v81
	v_add_f32_e32 v84, 1.0, v84
	v_add_f32_e32 v87, 1.0, v87
	v_rcp_f32_e32 v80, v80
	v_add_f32_e32 v85, 1.0, v85
	v_add_f32_e32 v89, 1.0, v89
	v_rcp_f32_e32 v81, v81
	v_rcp_f32_e32 v84, v84
	v_rcp_f32_e32 v87, v87
	v_add_f32_e32 v86, 1.0, v86
	v_add_f32_e32 v88, 1.0, v88
	v_rcp_f32_e32 v85, v85
	v_rcp_f32_e32 v89, v89
	v_rcp_f32_e32 v86, v86
	v_rcp_f32_e32 v88, v88
	v_mul_f32_e32 v80, v83, v80
	v_mul_f32_e32 v69, v69, v81
	v_mul_f32_e32 v77, v77, v84
	v_mul_f32_e32 v65, v65, v87
	v_mul_f32_e32 v80, v82, v80
	v_mul_f32_e32 v71, v71, v85
	v_mul_f32_e32 v67, v67, v89
	v_mul_f32_e32 v68, v68, v69
	v_mul_f32_e32 v69, v76, v77
	v_mul_f32_e32 v76, v64, v65
	v_cvt_pk_bf16_f32 v64, v80, v68
	v_add_u32_e32 v80, 0x80, v144
	v_mul_f32_e32 v79, v79, v86
	v_mul_f32_e32 v73, v73, v88
	v_mul_f32_e32 v70, v70, v71
	v_mul_f32_e32 v67, v66, v67
	v_cvt_pk_bf16_f32 v65, v69, v70
	v_ashrrev_i32_e32 v81, 31, v80
	v_mul_f32_e32 v71, v78, v79
	v_mul_f32_e32 v72, v72, v73
	v_cvt_pk_bf16_f32 v66, v71, v76
	v_cvt_pk_bf16_f32 v67, v72, v67
	global_store_dwordx4 v[74:75], v[64:67], off
	v_mov_b32_e32 v82, v60
	v_mov_b32_e32 v83, v52
	v_lshlrev_b64 v[64:65], 6, v[80:81]
	v_lshl_add_u64 v[76:77], s[10:11], 0, v[64:65]
	global_load_dwordx4 v[64:67], v[76:77], off
	global_load_dwordx4 v[68:71], v[76:77], off offset:16
	global_load_dwordx4 v[72:75], v[76:77], off offset:32
	s_nop 0
	global_load_dwordx4 v[76:79], v[76:77], off offset:48
	v_mov_b32_e32 v52, v61
	v_mov_b32_e32 v60, v62
	v_mov_b32_e32 v61, v54
	v_mov_b32_e32 v54, v63
	v_mov_b32_e32 v62, v56
	v_mov_b32_e32 v63, v48
	v_mov_b32_e32 v48, v57
	v_mov_b32_e32 v56, v58
	v_mov_b32_e32 v57, v50
	v_mov_b32_e32 v50, v59
	s_waitcnt vmcnt(3)
	v_mov_b32_e32 v58, v65
	v_mov_b32_e32 v59, v66
	v_mov_b32_e32 v65, v67
	s_waitcnt vmcnt(2)
	v_mov_b32_e32 v66, v69
	v_mov_b32_e32 v67, v70
	v_mov_b32_e32 v69, v71
	v_pk_add_f32 v[58:59], v[58:59], v[64:65]
	v_pk_add_f32 v[64:65], v[66:67], v[68:69]
	v_pk_add_f32 v[58:59], v[58:59], v[58:59] op_sel:[0,1] op_sel_hi:[1,0]
	v_pk_add_f32 v[64:65], v[64:65], v[64:65] op_sel:[0,1] op_sel_hi:[1,0]
	s_waitcnt vmcnt(1)
	v_add_f32_e32 v70, v72, v73
	v_add_f32_e32 v72, v74, v75
	s_waitcnt vmcnt(0)
	v_mov_b32_e32 v71, v78
	v_mov_b32_e32 v73, v79
	v_mov_b32_e32 v59, v76
	v_mov_b32_e32 v65, v77
	v_pk_add_f32 v[66:67], v[70:71], v[72:73]
	v_pk_add_f32 v[58:59], v[58:59], v[64:65]
	s_nop 0
	v_pk_add_f32 v[58:59], v[58:59], v[66:67]
	s_nop 0
	v_add_f32_e32 v58, v58, v59
	v_fmamk_f32 v58, v58, 0x3a800000, v152
	v_mul_f32_e32 v59, 0x4b800000, v58
	v_cmp_gt_f32_e32 vcc, s52, v58
	s_nop 1
	v_cndmask_b32_e32 v58, v58, v59, vcc
	v_rsq_f32_e32 v64, v58
	v_mad_i64_i32 v[58:59], s[26:27], v80, s53, v[120:121]
	v_lshl_add_u64 v[58:59], v[58:59], 0, v[122:123]
	v_mul_f32_e32 v65, 0x45800000, v64
	v_cndmask_b32_e32 v64, v64, v65, vcc
	v_pk_mul_f32 v[66:67], v[82:83], v[64:65] op_sel_hi:[1,0]
	v_pk_mul_f32 v[52:53], v[52:53], v[64:65] op_sel_hi:[1,0]
	v_pk_mul_f32 v[60:61], v[60:61], v[64:65] op_sel_hi:[1,0]
	v_pk_mul_f32 v[54:55], v[54:55], v[64:65] op_sel_hi:[1,0]
	v_pk_mul_f32 v[62:63], v[62:63], v[64:65] op_sel_hi:[1,0]
	v_pk_mul_f32 v[48:49], v[48:49], v[64:65] op_sel_hi:[1,0]
	v_pk_mul_f32 v[56:57], v[56:57], v[64:65] op_sel_hi:[1,0]
	v_pk_mul_f32 v[50:51], v[50:51], v[64:65] op_sel_hi:[1,0]
	v_mul_f32_e32 v64, 0xbfb8aa3b, v67
	v_mul_f32_e32 v65, 0xbfb8aa3b, v53
	v_mul_f32_e32 v68, 0xbfb8aa3b, v61
	v_mul_f32_e32 v71, 0xbfb8aa3b, v49
	v_exp_f32_e32 v64, v64
	v_mul_f32_e32 v69, 0xbfb8aa3b, v55
	v_mul_f32_e32 v73, 0xbfb8aa3b, v51
	v_exp_f32_e32 v65, v65
	v_exp_f32_e32 v68, v68
	v_exp_f32_e32 v71, v71
	v_mul_f32_e32 v70, 0xbfb8aa3b, v63
	v_mul_f32_e32 v72, 0xbfb8aa3b, v57
	v_exp_f32_e32 v69, v69
	v_exp_f32_e32 v73, v73
	v_exp_f32_e32 v70, v70
	v_exp_f32_e32 v72, v72
	v_add_f32_e32 v64, 1.0, v64
	v_add_f32_e32 v65, 1.0, v65
	v_add_f32_e32 v68, 1.0, v68
	v_add_f32_e32 v71, 1.0, v71
	v_rcp_f32_e32 v64, v64
	v_add_f32_e32 v69, 1.0, v69
	v_add_f32_e32 v73, 1.0, v73
	v_rcp_f32_e32 v65, v65
	v_rcp_f32_e32 v68, v68
	v_rcp_f32_e32 v71, v71
	v_add_f32_e32 v70, 1.0, v70
	v_add_f32_e32 v72, 1.0, v72
	v_rcp_f32_e32 v69, v69
	v_rcp_f32_e32 v73, v73
	v_rcp_f32_e32 v70, v70
	v_rcp_f32_e32 v72, v72
	v_mul_f32_e32 v64, v67, v64
	v_mul_f32_e32 v53, v53, v65
	v_mul_f32_e32 v61, v61, v68
	v_mul_f32_e32 v49, v49, v71
	v_mul_f32_e32 v64, v66, v64
	v_mul_f32_e32 v55, v55, v69
	v_mul_f32_e32 v51, v51, v73
	v_mul_f32_e32 v52, v52, v53
	v_mul_f32_e32 v53, v60, v61
	v_mul_f32_e32 v60, v48, v49
	v_cvt_pk_bf16_f32 v48, v64, v52
	v_add_u32_e32 v64, 0x90, v144
	v_mul_f32_e32 v63, v63, v70
	v_mul_f32_e32 v57, v57, v72
	v_mul_f32_e32 v54, v54, v55
	v_mul_f32_e32 v51, v50, v51
	v_cvt_pk_bf16_f32 v49, v53, v54
	v_ashrrev_i32_e32 v65, 31, v64
	v_mul_f32_e32 v55, v62, v63
	v_mul_f32_e32 v56, v56, v57
	v_cvt_pk_bf16_f32 v50, v55, v60
	v_cvt_pk_bf16_f32 v51, v56, v51
	global_store_dwordx4 v[58:59], v[48:51], off
	v_mov_b32_e32 v66, v44
	v_mov_b32_e32 v67, v36
	v_lshlrev_b64 v[48:49], 6, v[64:65]
	v_lshl_add_u64 v[60:61], s[10:11], 0, v[48:49]
	global_load_dwordx4 v[48:51], v[60:61], off
	global_load_dwordx4 v[52:55], v[60:61], off offset:16
	global_load_dwordx4 v[56:59], v[60:61], off offset:32
	s_nop 0
	global_load_dwordx4 v[60:63], v[60:61], off offset:48
	v_mov_b32_e32 v36, v45
	v_mov_b32_e32 v44, v46
	v_mov_b32_e32 v45, v38
	v_mov_b32_e32 v38, v47
	v_mov_b32_e32 v46, v40
	v_mov_b32_e32 v47, v32
	v_mov_b32_e32 v32, v41
	v_mov_b32_e32 v40, v42
	v_mov_b32_e32 v41, v34
	v_mov_b32_e32 v34, v43
	s_waitcnt vmcnt(3)
	v_mov_b32_e32 v42, v49
	v_mov_b32_e32 v43, v50
	v_mov_b32_e32 v49, v51
	s_waitcnt vmcnt(2)
	v_mov_b32_e32 v50, v53
	v_mov_b32_e32 v51, v54
	v_mov_b32_e32 v53, v55
	v_pk_add_f32 v[42:43], v[42:43], v[48:49]
	v_pk_add_f32 v[48:49], v[50:51], v[52:53]
	v_pk_add_f32 v[42:43], v[42:43], v[42:43] op_sel:[0,1] op_sel_hi:[1,0]
	v_pk_add_f32 v[48:49], v[48:49], v[48:49] op_sel:[0,1] op_sel_hi:[1,0]
	s_waitcnt vmcnt(1)
	v_add_f32_e32 v54, v56, v57
	v_add_f32_e32 v56, v58, v59
	s_waitcnt vmcnt(0)
	v_mov_b32_e32 v55, v62
	v_mov_b32_e32 v57, v63
	v_mov_b32_e32 v43, v60
	v_mov_b32_e32 v49, v61
	v_pk_add_f32 v[50:51], v[54:55], v[56:57]
	v_pk_add_f32 v[42:43], v[42:43], v[48:49]
	s_nop 0
	v_pk_add_f32 v[42:43], v[42:43], v[50:51]
	s_nop 0
	v_add_f32_e32 v42, v42, v43
	v_fmamk_f32 v42, v42, 0x3a800000, v152
	v_mul_f32_e32 v43, 0x4b800000, v42
	v_cmp_gt_f32_e32 vcc, s52, v42
	s_nop 1
	v_cndmask_b32_e32 v42, v42, v43, vcc
	v_rsq_f32_e32 v48, v42
	v_mad_i64_i32 v[42:43], s[26:27], v64, s53, v[120:121]
	v_lshl_add_u64 v[42:43], v[42:43], 0, v[122:123]
	v_mul_f32_e32 v49, 0x45800000, v48
	v_cndmask_b32_e32 v48, v48, v49, vcc
	v_pk_mul_f32 v[50:51], v[66:67], v[48:49] op_sel_hi:[1,0]
	v_pk_mul_f32 v[36:37], v[36:37], v[48:49] op_sel_hi:[1,0]
	v_pk_mul_f32 v[44:45], v[44:45], v[48:49] op_sel_hi:[1,0]
	v_pk_mul_f32 v[38:39], v[38:39], v[48:49] op_sel_hi:[1,0]
	v_pk_mul_f32 v[46:47], v[46:47], v[48:49] op_sel_hi:[1,0]
	v_pk_mul_f32 v[32:33], v[32:33], v[48:49] op_sel_hi:[1,0]
	v_pk_mul_f32 v[40:41], v[40:41], v[48:49] op_sel_hi:[1,0]
	v_pk_mul_f32 v[34:35], v[34:35], v[48:49] op_sel_hi:[1,0]
	v_mul_f32_e32 v48, 0xbfb8aa3b, v51
	v_mul_f32_e32 v49, 0xbfb8aa3b, v37
	v_mul_f32_e32 v52, 0xbfb8aa3b, v45
	v_mul_f32_e32 v55, 0xbfb8aa3b, v33
	v_exp_f32_e32 v48, v48
	v_mul_f32_e32 v53, 0xbfb8aa3b, v39
	v_mul_f32_e32 v57, 0xbfb8aa3b, v35
	v_exp_f32_e32 v49, v49
	v_exp_f32_e32 v52, v52
	v_exp_f32_e32 v55, v55
	v_mul_f32_e32 v54, 0xbfb8aa3b, v47
	v_mul_f32_e32 v56, 0xbfb8aa3b, v41
	v_exp_f32_e32 v53, v53
	v_exp_f32_e32 v57, v57
	v_exp_f32_e32 v54, v54
	v_exp_f32_e32 v56, v56
	v_add_f32_e32 v48, 1.0, v48
	v_add_f32_e32 v49, 1.0, v49
	v_add_f32_e32 v52, 1.0, v52
	v_add_f32_e32 v55, 1.0, v55
	v_rcp_f32_e32 v48, v48
	v_add_f32_e32 v53, 1.0, v53
	v_add_f32_e32 v57, 1.0, v57
	v_rcp_f32_e32 v49, v49
	v_rcp_f32_e32 v52, v52
	v_rcp_f32_e32 v55, v55
	v_add_f32_e32 v54, 1.0, v54
	v_add_f32_e32 v56, 1.0, v56
	v_rcp_f32_e32 v53, v53
	v_rcp_f32_e32 v57, v57
	v_rcp_f32_e32 v54, v54
	v_rcp_f32_e32 v56, v56
	v_mul_f32_e32 v48, v51, v48
	v_mul_f32_e32 v37, v37, v49
	v_mul_f32_e32 v45, v45, v52
	v_mul_f32_e32 v33, v33, v55
	v_mul_f32_e32 v48, v50, v48
	v_mul_f32_e32 v39, v39, v53
	v_mul_f32_e32 v35, v35, v57
	v_mul_f32_e32 v36, v36, v37
	v_mul_f32_e32 v37, v44, v45
	v_mul_f32_e32 v44, v32, v33
	v_cvt_pk_bf16_f32 v32, v48, v36
	v_add_u32_e32 v48, 0xa0, v144
	v_mul_f32_e32 v47, v47, v54
	v_mul_f32_e32 v41, v41, v56
	v_mul_f32_e32 v38, v38, v39
	v_mul_f32_e32 v35, v34, v35
	v_cvt_pk_bf16_f32 v33, v37, v38
	v_ashrrev_i32_e32 v49, 31, v48
	v_mul_f32_e32 v39, v46, v47
	v_mul_f32_e32 v40, v40, v41
	v_cvt_pk_bf16_f32 v34, v39, v44
	v_cvt_pk_bf16_f32 v35, v40, v35
	global_store_dwordx4 v[42:43], v[32:35], off
	v_mov_b32_e32 v50, v28
	v_mov_b32_e32 v51, v20
	v_lshlrev_b64 v[32:33], 6, v[48:49]
	v_lshl_add_u64 v[44:45], s[10:11], 0, v[32:33]
	global_load_dwordx4 v[32:35], v[44:45], off
	global_load_dwordx4 v[36:39], v[44:45], off offset:16
	global_load_dwordx4 v[40:43], v[44:45], off offset:32
	s_nop 0
	global_load_dwordx4 v[44:47], v[44:45], off offset:48
	v_mov_b32_e32 v20, v29
	v_mov_b32_e32 v28, v30
	v_mov_b32_e32 v29, v22
	v_mov_b32_e32 v22, v31
	v_mov_b32_e32 v30, v24
	v_mov_b32_e32 v31, v16
	v_mov_b32_e32 v16, v25
	v_mov_b32_e32 v24, v26
	v_mov_b32_e32 v25, v18
	v_mov_b32_e32 v18, v27
	s_waitcnt vmcnt(3)
	v_mov_b32_e32 v26, v33
	v_mov_b32_e32 v27, v34
	v_mov_b32_e32 v33, v35
	s_waitcnt vmcnt(2)
	v_mov_b32_e32 v34, v37
	v_mov_b32_e32 v35, v38
	v_mov_b32_e32 v37, v39
	v_pk_add_f32 v[26:27], v[26:27], v[32:33]
	v_pk_add_f32 v[32:33], v[34:35], v[36:37]
	v_pk_add_f32 v[26:27], v[26:27], v[26:27] op_sel:[0,1] op_sel_hi:[1,0]
	v_pk_add_f32 v[32:33], v[32:33], v[32:33] op_sel:[0,1] op_sel_hi:[1,0]
	s_waitcnt vmcnt(1)
	v_add_f32_e32 v38, v40, v41
	v_add_f32_e32 v40, v42, v43
	s_waitcnt vmcnt(0)
	v_mov_b32_e32 v39, v46
	v_mov_b32_e32 v41, v47
	v_mov_b32_e32 v27, v44
	v_mov_b32_e32 v33, v45
	v_pk_add_f32 v[34:35], v[38:39], v[40:41]
	v_pk_add_f32 v[26:27], v[26:27], v[32:33]
	s_nop 0
	v_pk_add_f32 v[26:27], v[26:27], v[34:35]
	s_nop 0
	v_add_f32_e32 v26, v26, v27
	v_fmamk_f32 v26, v26, 0x3a800000, v152
	v_mul_f32_e32 v27, 0x4b800000, v26
	v_cmp_gt_f32_e32 vcc, s52, v26
	s_nop 1
	v_cndmask_b32_e32 v26, v26, v27, vcc
	v_rsq_f32_e32 v32, v26
	v_mad_i64_i32 v[26:27], s[26:27], v48, s53, v[120:121]
	v_lshl_add_u64 v[26:27], v[26:27], 0, v[122:123]
	v_mul_f32_e32 v33, 0x45800000, v32
	v_cndmask_b32_e32 v32, v32, v33, vcc
	v_pk_mul_f32 v[34:35], v[50:51], v[32:33] op_sel_hi:[1,0]
	v_pk_mul_f32 v[20:21], v[20:21], v[32:33] op_sel_hi:[1,0]
	v_pk_mul_f32 v[28:29], v[28:29], v[32:33] op_sel_hi:[1,0]
	v_pk_mul_f32 v[22:23], v[22:23], v[32:33] op_sel_hi:[1,0]
	v_pk_mul_f32 v[30:31], v[30:31], v[32:33] op_sel_hi:[1,0]
	v_pk_mul_f32 v[16:17], v[16:17], v[32:33] op_sel_hi:[1,0]
	v_pk_mul_f32 v[24:25], v[24:25], v[32:33] op_sel_hi:[1,0]
	v_pk_mul_f32 v[18:19], v[18:19], v[32:33] op_sel_hi:[1,0]
	v_mul_f32_e32 v32, 0xbfb8aa3b, v35
	v_mul_f32_e32 v33, 0xbfb8aa3b, v21
	v_mul_f32_e32 v36, 0xbfb8aa3b, v29
	v_mul_f32_e32 v39, 0xbfb8aa3b, v17
	v_exp_f32_e32 v32, v32
	v_mul_f32_e32 v37, 0xbfb8aa3b, v23
	v_mul_f32_e32 v41, 0xbfb8aa3b, v19
	v_exp_f32_e32 v33, v33
	v_exp_f32_e32 v36, v36
	v_exp_f32_e32 v39, v39
	v_mul_f32_e32 v38, 0xbfb8aa3b, v31
	v_mul_f32_e32 v40, 0xbfb8aa3b, v25
	v_exp_f32_e32 v37, v37
	v_exp_f32_e32 v41, v41
	v_exp_f32_e32 v38, v38
	v_exp_f32_e32 v40, v40
	v_add_f32_e32 v32, 1.0, v32
	v_add_f32_e32 v33, 1.0, v33
	v_add_f32_e32 v36, 1.0, v36
	v_add_f32_e32 v39, 1.0, v39
	v_rcp_f32_e32 v32, v32
	v_add_f32_e32 v37, 1.0, v37
	v_add_f32_e32 v41, 1.0, v41
	v_rcp_f32_e32 v33, v33
	v_rcp_f32_e32 v36, v36
	v_rcp_f32_e32 v39, v39
	v_add_f32_e32 v38, 1.0, v38
	v_add_f32_e32 v40, 1.0, v40
	v_rcp_f32_e32 v37, v37
	v_rcp_f32_e32 v41, v41
	v_rcp_f32_e32 v38, v38
	v_rcp_f32_e32 v40, v40
	v_mul_f32_e32 v32, v35, v32
	v_mul_f32_e32 v21, v21, v33
	v_mul_f32_e32 v29, v29, v36
	v_mul_f32_e32 v17, v17, v39
	v_mul_f32_e32 v32, v34, v32
	v_mul_f32_e32 v23, v23, v37
	v_mul_f32_e32 v19, v19, v41
	v_mul_f32_e32 v20, v20, v21
	v_mul_f32_e32 v21, v28, v29
	v_mul_f32_e32 v28, v16, v17
	v_cvt_pk_bf16_f32 v16, v32, v20
	v_add_u32_e32 v32, 0xb0, v144
	v_mul_f32_e32 v31, v31, v38
	v_mul_f32_e32 v25, v25, v40
	v_mul_f32_e32 v22, v22, v23
	v_mul_f32_e32 v19, v18, v19
	v_cvt_pk_bf16_f32 v17, v21, v22
	v_ashrrev_i32_e32 v33, 31, v32
	v_mul_f32_e32 v23, v30, v31
	v_mul_f32_e32 v24, v24, v25
	v_cvt_pk_bf16_f32 v18, v23, v28
	v_cvt_pk_bf16_f32 v19, v24, v19
	global_store_dwordx4 v[26:27], v[16:19], off
	v_mov_b32_e32 v34, v12
	v_mov_b32_e32 v35, v4
	v_lshlrev_b64 v[16:17], 6, v[32:33]
	v_lshl_add_u64 v[28:29], s[10:11], 0, v[16:17]
	global_load_dwordx4 v[16:19], v[28:29], off
	global_load_dwordx4 v[20:23], v[28:29], off offset:16
	global_load_dwordx4 v[24:27], v[28:29], off offset:32
	s_nop 0
	global_load_dwordx4 v[28:31], v[28:29], off offset:48
	v_mov_b32_e32 v4, v13
	v_mov_b32_e32 v12, v14
	v_mov_b32_e32 v13, v6
	v_mov_b32_e32 v6, v15
	v_mov_b32_e32 v14, v8
	v_mov_b32_e32 v15, v0
	v_mov_b32_e32 v0, v9
	v_mov_b32_e32 v8, v10
	v_mov_b32_e32 v9, v2
	v_mov_b32_e32 v2, v11
	s_waitcnt vmcnt(3)
	v_mov_b32_e32 v10, v17
	v_mov_b32_e32 v11, v18
	v_mov_b32_e32 v17, v19
	s_waitcnt vmcnt(2)
	v_mov_b32_e32 v18, v21
	v_mov_b32_e32 v19, v22
	v_mov_b32_e32 v21, v23
	v_pk_add_f32 v[10:11], v[10:11], v[16:17]
	v_pk_add_f32 v[16:17], v[18:19], v[20:21]
	v_pk_add_f32 v[10:11], v[10:11], v[10:11] op_sel:[0,1] op_sel_hi:[1,0]
	v_pk_add_f32 v[16:17], v[16:17], v[16:17] op_sel:[0,1] op_sel_hi:[1,0]
	s_waitcnt vmcnt(1)
	v_add_f32_e32 v22, v24, v25
	v_add_f32_e32 v24, v26, v27
	s_waitcnt vmcnt(0)
	v_mov_b32_e32 v23, v30
	v_mov_b32_e32 v25, v31
	v_mov_b32_e32 v11, v28
	v_mov_b32_e32 v17, v29
	v_pk_add_f32 v[18:19], v[22:23], v[24:25]
	v_pk_add_f32 v[10:11], v[10:11], v[16:17]
	s_nop 0
	v_pk_add_f32 v[10:11], v[10:11], v[18:19]
	s_nop 0
	v_add_f32_e32 v10, v10, v11
	v_fmamk_f32 v10, v10, 0x3a800000, v152
	v_mul_f32_e32 v11, 0x4b800000, v10
	v_cmp_gt_f32_e32 vcc, s52, v10
	s_nop 1
	v_cndmask_b32_e32 v10, v10, v11, vcc
	v_rsq_f32_e32 v16, v10
	v_mad_i64_i32 v[10:11], s[26:27], v32, s53, v[120:121]
	v_lshl_add_u64 v[10:11], v[10:11], 0, v[122:123]
	v_mul_f32_e32 v17, 0x45800000, v16
	v_cndmask_b32_e32 v16, v16, v17, vcc
	v_pk_mul_f32 v[2:3], v[2:3], v[16:17] op_sel_hi:[1,0]
	v_pk_mul_f32 v[18:19], v[34:35], v[16:17] op_sel_hi:[1,0]
	v_pk_mul_f32 v[4:5], v[4:5], v[16:17] op_sel_hi:[1,0]
	v_pk_mul_f32 v[12:13], v[12:13], v[16:17] op_sel_hi:[1,0]
	v_pk_mul_f32 v[6:7], v[6:7], v[16:17] op_sel_hi:[1,0]
	v_pk_mul_f32 v[14:15], v[14:15], v[16:17] op_sel_hi:[1,0]
	v_pk_mul_f32 v[0:1], v[0:1], v[16:17] op_sel_hi:[1,0]
	v_pk_mul_f32 v[8:9], v[8:9], v[16:17] op_sel_hi:[1,0]
	v_mul_f32_e32 v25, 0xbfb8aa3b, v3
	v_mul_f32_e32 v16, 0xbfb8aa3b, v19
	v_mul_f32_e32 v17, 0xbfb8aa3b, v5
	v_mul_f32_e32 v20, 0xbfb8aa3b, v13
	v_mul_f32_e32 v21, 0xbfb8aa3b, v7
	v_mul_f32_e32 v22, 0xbfb8aa3b, v15
	v_mul_f32_e32 v23, 0xbfb8aa3b, v1
	v_mul_f32_e32 v24, 0xbfb8aa3b, v9
	v_exp_f32_e32 v25, v25
	v_exp_f32_e32 v16, v16
	v_exp_f32_e32 v17, v17
	v_exp_f32_e32 v20, v20
	v_exp_f32_e32 v21, v21
	v_exp_f32_e32 v22, v22
	v_exp_f32_e32 v23, v23
	v_exp_f32_e32 v24, v24
	v_add_f32_e32 v25, 1.0, v25
	v_add_f32_e32 v16, 1.0, v16
	v_add_f32_e32 v17, 1.0, v17
	v_add_f32_e32 v20, 1.0, v20
	v_add_f32_e32 v21, 1.0, v21
	v_add_f32_e32 v22, 1.0, v22
	v_add_f32_e32 v23, 1.0, v23
	v_add_f32_e32 v24, 1.0, v24
	v_rcp_f32_e32 v25, v25
	v_rcp_f32_e32 v16, v16
	v_rcp_f32_e32 v17, v17
	v_rcp_f32_e32 v20, v20
	v_rcp_f32_e32 v21, v21
	v_rcp_f32_e32 v22, v22
	v_rcp_f32_e32 v23, v23
	v_rcp_f32_e32 v24, v24
	v_mul_f32_e32 v3, v3, v25
	v_mul_f32_e32 v16, v19, v16
	v_mul_f32_e32 v5, v5, v17
	v_mul_f32_e32 v13, v13, v20
	v_mul_f32_e32 v7, v7, v21
	v_mul_f32_e32 v15, v15, v22
	v_mul_f32_e32 v1, v1, v23
	v_mul_f32_e32 v9, v9, v24
	v_mul_f32_e32 v3, v2, v3
	s_andn2_b64 vcc, exec, s[6:7]
	s_mov_b64 s[6:7], -1
	v_mul_f32_e32 v16, v18, v16
	v_mul_f32_e32 v4, v4, v5
	v_mul_f32_e32 v5, v12, v13
	v_mul_f32_e32 v6, v6, v7
	v_mul_f32_e32 v7, v14, v15
	v_mul_f32_e32 v12, v0, v1
	v_mul_f32_e32 v8, v8, v9
	v_cvt_pk_bf16_f32 v0, v16, v4
	v_cvt_pk_bf16_f32 v1, v5, v6
	v_cvt_pk_bf16_f32 v2, v7, v12
	v_cvt_pk_bf16_f32 v3, v8, v3
	global_store_dwordx4 v[10:11], v[0:3], off
	s_cbranch_vccnz .LBB0_3315
	s_andn2_b64 vcc, exec, s[0:1]
	s_cbranch_vccnz .LBB0_3314
	s_barrier
	s_branch .LBB0_3314

.LBB0_3326:
	s_cmp_eq_u32 s100, 1
	s_cbranch_scc0 .Lgb_full_9
	s_waitcnt vmcnt(0)
	s_barrier
	s_and_saveexec_b64 s[0:1], s[46:47]
	s_cbranch_execz .Lgb_done_9
	s_and_b32 s98, s2, 7
	s_lshl_b32 s98, s98, 6
	s_add_i32 s98, s98, 0x4a00
	v_mov_b32_e32 v250, s98
	v_mov_b32_e32 v251, 1
	global_atomic_add v252, v250, v251, s[66:67] sc0
	buffer_inv sc1
	s_lshr_b32 s98, s64, 3
	s_mul_i32 s98, s98, 10
	s_add_i32 s98, s98, -1
	v_add_u32_e32 v250, 0x200, v250
	s_waitcnt vmcnt(0)
	v_readfirstlane_b32 s99, v252
	s_cmp_eq_u32 s99, s98
	s_cbranch_scc0 .Lgb_wait_9
	global_atomic_add v250, v251, s[66:67]
	s_waitcnt vmcnt(0)
	s_branch .Lgb_done_9

.Lgb_spin_9:
	global_load_dword v252, v250, s[66:67] sc1
	s_waitcnt vmcnt(0)
	v_readfirstlane_b32 s98, v252
	s_cmp_gt_u32 s98, 9
	s_cbranch_scc1 .Lgb_done_9
	s_sleep 1
	s_add_i32 s99, s99, 1
	s_cmp_lt_u32 s99, 0x8000
	s_cbranch_scc1 .Lgb_spin_9
